# GEMM: first K-iteration peeled with zero C operand; per-tile accumulator zeroing (128 v_mov) removed
# speedup vs baseline: 1.0066x; 1.0019x over previous
; #define PG8_STAGE(bufoff, gbase, voff) do { _Pragma("unroll") for (int _i = 0; _i < 2; ++_i) \
;         __builtin_amdgcn_global_load_lds((const unsigned*)((const char*)(gbase) + (voff)[_i]), (PG8_LAS unsigned*)(lds + (bufoff) + ldsw + _i * 8192), 16, 0, 0); } while (0)
; #define PG8_LDA(dst, b, h) do { _Pragma("unroll") for (int m = 0; m < 4; ++m) _Pragma("unroll") for (int k = 0; k < 2; ++k) dst[m][k] = *(const PG8_LAS bf16x8*)(lds + PG8_SA(b, h) + aoff + m * 2048 + k * 1024); } while (0)
; #define PG8_LDB(dst, b, h) do { _Pragma("unroll") for (int n = 0; n < 2; ++n) _Pragma("unroll") for (int k = 0; k < 2; ++k) dst[n][k] = *(const PG8_LAS bf16x8*)(lds + PG8_SB(b, h) + boff + n * 2048 + k * 1024); } while (0)
; #define PG8_MMA(ai, bj, At, Bt) do { __builtin_amdgcn_s_setprio(1); _Pragma("unroll") for (int m = 0; m < 4; ++m) _Pragma("unroll") for (int n = 0; n < 2; ++n) _Pragma("unroll") for (int k = 0; k < 2; ++k) \
;         acc[ai][bj][m][n] = __builtin_amdgcn_mfma_f32_16x16x32_bf16(Bt[n][k], At[m][k], acc[ai][bj][m][n], 0, 0, 0); __builtin_amdgcn_s_setprio(0); } while (0)
; #define PG8_WAIT_V(n) asm volatile("s_waitcnt vmcnt(" #n ")" ::: "memory")
; #define PG8_BAR __builtin_amdgcn_s_barrier()
; template <class Epi, class Sched, bool STAMP = false>
; __device__ __forceinline__ void gemm_phase(PG8_LAS unsigned char* lds, const Gemm g, const Sched& S, const Epi& E, unsigned long long* stamps) {
;     ...
;             PG8_LDB(B0, 0, 0); PG8_SCHED; PG8_LDA(At, 0, 0); PG8_STAGE(PG8_SA(1, 1), a1 + hstep, voffA);
;             PG8_WAIT_L(8); PG8_BAR; PG8_WAIT_L(0); PG8_MMA(0, 0, At, B0); PG8_BAR; PG8_SCHED;
;             PG8_LDB(B1, 0, 1); PG8_STAGE(PG8_SB(0, 0), b2, voffB);
;             PG8_BAR; PG8_WAIT_L(0); PG8_MMA(0, 1, At, B1); PG8_BAR;
;             PG8_LDA(At, 0, 1); PG8_STAGE(PG8_SA(0, 0), a2, voffA);
;             PG8_BAR; PG8_WAIT_L(0); PG8_MMA(1, 0, At, B0); PG8_BAR; PG8_SCHED;
;             PG8_STAGE(PG8_SB(0, 1), b2 + hstep, voffB);
;             PG8_WAIT_V(6); PG8_BAR; PG8_MMA(1, 1, At, B1); PG8_BAR;
;     ...
; #pragma unroll
;         for (int a = 0; a < 2; ++a)
; #pragma unroll
;             for (int b = 0; b < 2; ++b)
; #pragma unroll
;                 for (int m = 0; m < 4; ++m)
; #pragma unroll
;                     for (int n = 0; n < 2; ++n) acc[a][b][m][n] = (f32x4){0.f, 0.f, 0.f, 0.f};
;         cur = nxt; cA = nA; cB = nB; ++ui;
.LBB0_744:
	s_add_u32 s0, s22, 0x80
	s_addc_u32 s1, s23, 0
	s_add_u32 s88, s88, 0x100
	s_addc_u32 s89, s89, 0
	s_mov_b32 s22, 0
.Lg_peel:
	s_add_i32 s93, s22, 2
	s_add_u32 s38, s0, 0x80
	s_addc_u32 s23, s1, 0
	s_add_i32 s62, 0, 0x10000
	v_add_u32_e32 v142, s62, v217
	ds_read_b128 v[130:133], v142
	ds_read_b128 v[134:137], v142 offset:1024
	ds_read_b128 v[138:141], v142 offset:2048
	ds_read_b128 v[142:145], v142 offset:3072
	s_cmp_eq_u32 s4, s22
	s_cselect_b32 s22, s90, s38
	s_cselect_b32 s23, s91, s23
	s_cselect_b32 s39, s31, s89
	s_cselect_b32 s38, s30, s88
	s_add_i32 m0, s80, 0xc000
	ds_read_b128 v[146:149], v218
	ds_read_b128 v[150:153], v218 offset:1024
	ds_read_b128 v[154:157], v218 offset:2048
	ds_read_b128 v[158:161], v218 offset:3072
	ds_read_b128 v[176:179], v218 offset:4096
	ds_read_b128 v[180:183], v218 offset:5120
	ds_read_b128 v[184:187], v218 offset:6144
	ds_read_b128 v[188:191], v218 offset:7168
	global_load_lds_dwordx4 v172, s[0:1]
	s_add_i32 m0, s80, 0xe000
	s_nop 0
	global_load_lds_dwordx4 v174, s[0:1]
	s_waitcnt lgkmcnt(8)
	s_barrier
	s_waitcnt lgkmcnt(0)
	s_waitcnt lgkmcnt(0)
	v_mfma_f32_16x16x32_bf16 v[126:129], v[130:133], v[146:149], 0
	v_mfma_f32_16x16x32_bf16 v[122:125], v[138:141], v[146:149], 0
	v_mfma_f32_16x16x32_bf16 v[118:121], v[130:133], v[154:157], 0
	v_mfma_f32_16x16x32_bf16 v[114:117], v[138:141], v[154:157], 0
	v_mfma_f32_16x16x32_bf16 v[102:105], v[130:133], v[176:179], 0
	v_mfma_f32_16x16x32_bf16 v[98:101], v[138:141], v[176:179], 0
	v_mfma_f32_16x16x32_bf16 v[86:89], v[130:133], v[184:187], 0
	v_mfma_f32_16x16x32_bf16 v[82:85], v[138:141], v[184:187], 0
	v_mfma_f32_16x16x32_bf16 v[126:129], v[134:137], v[150:153], v[126:129]
	v_mfma_f32_16x16x32_bf16 v[122:125], v[142:145], v[150:153], v[122:125]
	v_mfma_f32_16x16x32_bf16 v[118:121], v[134:137], v[158:161], v[118:121]
	v_mfma_f32_16x16x32_bf16 v[114:117], v[142:145], v[158:161], v[114:117]
	v_mfma_f32_16x16x32_bf16 v[102:105], v[134:137], v[180:183], v[102:105]
	v_mfma_f32_16x16x32_bf16 v[98:101], v[142:145], v[180:183], v[98:101]
	v_mfma_f32_16x16x32_bf16 v[86:89], v[134:137], v[188:191], v[86:89]
	v_mfma_f32_16x16x32_bf16 v[82:85], v[142:145], v[188:191], v[82:85]
	s_barrier
	s_add_i32 s63, 0, 0x14000
	s_add_i32 s62, s62, s79
	v_add_u32_e32 v204, s63, v217
	s_add_u32 s98, s38, s10
	s_addc_u32 s99, s39, s11
	s_mov_b32 m0, s62
	ds_read_b128 v[192:195], v204
	ds_read_b128 v[196:199], v204 offset:1024
	ds_read_b128 v[200:203], v204 offset:2048
	ds_read_b128 v[204:207], v204 offset:3072
	global_load_lds_dwordx4 v164, s[38:39]
	s_add_i32 m0, s62, 0x2000
	s_nop 0
	global_load_lds_dwordx4 v170, s[38:39]
	s_barrier
	s_waitcnt lgkmcnt(0)
	s_waitcnt lgkmcnt(0)
	v_mfma_f32_16x16x32_bf16 v[110:113], v[192:195], v[146:149], 0
	v_mfma_f32_16x16x32_bf16 v[106:109], v[200:203], v[146:149], 0
	v_mfma_f32_16x16x32_bf16 v[94:97], v[192:195], v[154:157], 0
	v_mfma_f32_16x16x32_bf16 v[90:93], v[200:203], v[154:157], 0
	v_mfma_f32_16x16x32_bf16 v[78:81], v[192:195], v[176:179], 0
	v_mfma_f32_16x16x32_bf16 v[74:77], v[200:203], v[176:179], 0
	v_mfma_f32_16x16x32_bf16 v[70:73], v[192:195], v[184:187], 0
	v_mfma_f32_16x16x32_bf16 v[66:69], v[200:203], v[184:187], 0
	v_mfma_f32_16x16x32_bf16 v[110:113], v[196:199], v[150:153], v[110:113]
	v_mfma_f32_16x16x32_bf16 v[106:109], v[204:207], v[150:153], v[106:109]
	v_mfma_f32_16x16x32_bf16 v[94:97], v[196:199], v[158:161], v[94:97]
	v_mfma_f32_16x16x32_bf16 v[90:93], v[204:207], v[158:161], v[90:93]
	v_mfma_f32_16x16x32_bf16 v[78:81], v[196:199], v[180:183], v[78:81]
	v_mfma_f32_16x16x32_bf16 v[74:77], v[204:207], v[180:183], v[74:77]
	v_mfma_f32_16x16x32_bf16 v[70:73], v[196:199], v[188:191], v[70:73]
	v_mfma_f32_16x16x32_bf16 v[66:69], v[204:207], v[188:191], v[66:69]
	s_mov_b32 m0, s80
	s_add_u32 s100, s22, s10
	s_addc_u32 s101, s23, s11
	s_barrier
	ds_read_b128 v[146:149], v218 offset:16384
	ds_read_b128 v[150:153], v218 offset:17408
	ds_read_b128 v[154:157], v218 offset:18432
	ds_read_b128 v[158:161], v218 offset:19456
	ds_read_b128 v[176:179], v218 offset:20480
	ds_read_b128 v[180:183], v218 offset:21504
	ds_read_b128 v[184:187], v218 offset:22528
	ds_read_b128 v[188:191], v218 offset:23552
	global_load_lds_dwordx4 v162, s[22:23]
	s_mov_b32 m0, s81
	s_nop 0
	global_load_lds_dwordx4 v166, s[22:23]
	s_barrier
	s_waitcnt lgkmcnt(0)
	s_waitcnt lgkmcnt(0)
	v_mfma_f32_16x16x32_bf16 v[62:65], v[130:133], v[146:149], 0
	v_mfma_f32_16x16x32_bf16 v[58:61], v[138:141], v[146:149], 0
	v_mfma_f32_16x16x32_bf16 v[54:57], v[130:133], v[154:157], 0
	v_mfma_f32_16x16x32_bf16 v[50:53], v[138:141], v[154:157], 0
	v_mfma_f32_16x16x32_bf16 v[38:41], v[130:133], v[176:179], 0
	v_mfma_f32_16x16x32_bf16 v[34:37], v[138:141], v[176:179], 0
	v_mfma_f32_16x16x32_bf16 v[22:25], v[130:133], v[184:187], 0
	v_mfma_f32_16x16x32_bf16 v[18:21], v[138:141], v[184:187], 0
	v_mfma_f32_16x16x32_bf16 v[62:65], v[134:137], v[150:153], v[62:65]
	v_mfma_f32_16x16x32_bf16 v[58:61], v[142:145], v[150:153], v[58:61]
	v_mfma_f32_16x16x32_bf16 v[54:57], v[134:137], v[158:161], v[54:57]
	v_mfma_f32_16x16x32_bf16 v[50:53], v[142:145], v[158:161], v[50:53]
	v_mfma_f32_16x16x32_bf16 v[38:41], v[134:137], v[180:183], v[38:41]
	v_mfma_f32_16x16x32_bf16 v[34:37], v[142:145], v[180:183], v[34:37]
	v_mfma_f32_16x16x32_bf16 v[22:25], v[134:137], v[188:191], v[22:25]
	v_mfma_f32_16x16x32_bf16 v[18:21], v[142:145], v[188:191], v[18:21]
	s_barrier
	s_add_u32 s38, s38, s94
	s_addc_u32 s39, s39, 0
	s_add_i32 s62, s63, s79
	s_mov_b32 m0, s62
	global_load_lds_dwordx4 v164, s[38:39]
	s_add_i32 m0, s62, 0x2000
	s_nop 0
	global_load_lds_dwordx4 v170, s[38:39]
	s_waitcnt vmcnt(6)
	s_barrier
; #define PG8_STAGE(bufoff, gbase, voff) do { _Pragma("unroll") for (int _i = 0; _i < 2; ++_i) \
;         __builtin_amdgcn_global_load_lds((const unsigned*)((const char*)(gbase) + (voff)[_i]), (PG8_LAS unsigned*)(lds + (bufoff) + ldsw + _i * 8192), 16, 0, 0); } while (0)
; #define PG8_LDA(dst, b, h) do { _Pragma("unroll") for (int m = 0; m < 4; ++m) _Pragma("unroll") for (int k = 0; k < 2; ++k) dst[m][k] = *(const PG8_LAS bf16x8*)(lds + PG8_SA(b, h) + aoff + m * 2048 + k * 1024); } while (0)
; #define PG8_LDB(dst, b, h) do { _Pragma("unroll") for (int n = 0; n < 2; ++n) _Pragma("unroll") for (int k = 0; k < 2; ++k) dst[n][k] = *(const PG8_LAS bf16x8*)(lds + PG8_SB(b, h) + boff + n * 2048 + k * 1024); } while (0)
; #define PG8_MMA(ai, bj, At, Bt) do { __builtin_amdgcn_s_setprio(1); _Pragma("unroll") for (int m = 0; m < 4; ++m) _Pragma("unroll") for (int n = 0; n < 2; ++n) _Pragma("unroll") for (int k = 0; k < 2; ++k) \
;         acc[ai][bj][m][n] = __builtin_amdgcn_mfma_f32_16x16x32_bf16(Bt[n][k], At[m][k], acc[ai][bj][m][n], 0, 0, 0); __builtin_amdgcn_s_setprio(0); } while (0)
; #define PG8_WAIT_V(n) asm volatile("s_waitcnt vmcnt(" #n ")" ::: "memory")
; #define PG8_WAIT_L(n) asm volatile("s_waitcnt lgkmcnt(" #n ")" ::: "memory")
; #define PG8_BAR __builtin_amdgcn_s_barrier()
; #define PG8_SCHED __builtin_amdgcn_sched_barrier(0)
; template <class Epi, class Sched, bool STAMP = false>
; __device__ __forceinline__ void gemm_phase(PG8_LAS unsigned char* lds, const Gemm g, const Sched& S, const Epi& E, unsigned long long* stamps) {
;     ...
;             PG8_WAIT_V(6); PG8_BAR; PG8_MMA(1, 1, At, B1); PG8_BAR;
;             PG8_LDB(B0, 1, 0); PG8_SCHED; PG8_LDA(At, 1, 0); PG8_STAGE(PG8_SA(0, 1), a2 + hstep, voffA);
;             PG8_WAIT_L(8); PG8_BAR; PG8_WAIT_L(0); PG8_MMA(0, 0, At, B0); PG8_BAR; PG8_SCHED;
;             PG8_LDB(B1, 1, 1); PG8_STAGE(PG8_SB(1, 0), b3, voffB);
;             PG8_BAR; PG8_WAIT_L(0); PG8_MMA(0, 1, At, B1); PG8_BAR;
;             PG8_LDA(At, 1, 1); PG8_STAGE(PG8_SA(1, 0), a3, voffA);
;             PG8_BAR; PG8_WAIT_L(0); PG8_MMA(1, 0, At, B0); PG8_BAR; PG8_SCHED;
	v_mfma_f32_16x16x32_bf16 v[46:49], v[192:195], v[146:149], 0
	v_mfma_f32_16x16x32_bf16 v[42:45], v[200:203], v[146:149], 0
	v_mfma_f32_16x16x32_bf16 v[30:33], v[192:195], v[154:157], 0
	v_mfma_f32_16x16x32_bf16 v[26:29], v[200:203], v[154:157], 0
	v_mfma_f32_16x16x32_bf16 v[14:17], v[192:195], v[176:179], 0
	v_mfma_f32_16x16x32_bf16 v[10:13], v[200:203], v[176:179], 0
	v_mfma_f32_16x16x32_bf16 v[6:9], v[192:195], v[184:187], 0
	v_mfma_f32_16x16x32_bf16 v[2:5], v[200:203], v[184:187], 0
	v_mfma_f32_16x16x32_bf16 v[46:49], v[196:199], v[150:153], v[46:49]
	v_mfma_f32_16x16x32_bf16 v[42:45], v[204:207], v[150:153], v[42:45]
	v_mfma_f32_16x16x32_bf16 v[30:33], v[196:199], v[158:161], v[30:33]
	v_mfma_f32_16x16x32_bf16 v[26:29], v[204:207], v[158:161], v[26:29]
	v_mfma_f32_16x16x32_bf16 v[14:17], v[196:199], v[180:183], v[14:17]
	v_mfma_f32_16x16x32_bf16 v[10:13], v[204:207], v[180:183], v[10:13]
	v_mfma_f32_16x16x32_bf16 v[6:9], v[196:199], v[188:191], v[6:9]
	v_mfma_f32_16x16x32_bf16 v[2:5], v[204:207], v[188:191], v[2:5]
	s_add_i32 s38, 0, 0x18000
	v_add_u32_e32 v142, s38, v217
	s_barrier
	ds_read_b128 v[130:133], v142
	ds_read_b128 v[134:137], v142 offset:1024
	ds_read_b128 v[138:141], v142 offset:2048
	ds_read_b128 v[142:145], v142 offset:3072
	s_add_u32 s22, s22, s94
	s_addc_u32 s23, s23, 0
	s_mov_b32 m0, s84
	ds_read_b128 v[146:149], v218 offset:32768
	ds_read_b128 v[150:153], v218 offset:33792
	ds_read_b128 v[154:157], v218 offset:34816
	ds_read_b128 v[158:161], v218 offset:35840
	ds_read_b128 v[176:179], v218 offset:36864
	ds_read_b128 v[180:183], v218 offset:37888
	ds_read_b128 v[184:187], v218 offset:38912
	ds_read_b128 v[188:191], v218 offset:39936
	global_load_lds_dwordx4 v162, s[22:23]
	s_mov_b32 m0, s85
	s_nop 0
	global_load_lds_dwordx4 v166, s[22:23]
	s_waitcnt lgkmcnt(8)
	s_barrier
	s_waitcnt lgkmcnt(0)
	s_waitcnt lgkmcnt(0)
	v_mfma_f32_16x16x32_bf16 v[126:129], v[130:133], v[146:149], v[126:129]
	v_mfma_f32_16x16x32_bf16 v[122:125], v[138:141], v[146:149], v[122:125]
	v_mfma_f32_16x16x32_bf16 v[118:121], v[130:133], v[154:157], v[118:121]
	v_mfma_f32_16x16x32_bf16 v[114:117], v[138:141], v[154:157], v[114:117]
	v_mfma_f32_16x16x32_bf16 v[102:105], v[130:133], v[176:179], v[102:105]
	v_mfma_f32_16x16x32_bf16 v[98:101], v[138:141], v[176:179], v[98:101]
	v_mfma_f32_16x16x32_bf16 v[86:89], v[130:133], v[184:187], v[86:89]
	v_mfma_f32_16x16x32_bf16 v[82:85], v[138:141], v[184:187], v[82:85]
	v_mfma_f32_16x16x32_bf16 v[126:129], v[134:137], v[150:153], v[126:129]
	v_mfma_f32_16x16x32_bf16 v[122:125], v[142:145], v[150:153], v[122:125]
	v_mfma_f32_16x16x32_bf16 v[118:121], v[134:137], v[158:161], v[118:121]
	v_mfma_f32_16x16x32_bf16 v[114:117], v[142:145], v[158:161], v[114:117]
	v_mfma_f32_16x16x32_bf16 v[102:105], v[134:137], v[180:183], v[102:105]
	v_mfma_f32_16x16x32_bf16 v[98:101], v[142:145], v[180:183], v[98:101]
	v_mfma_f32_16x16x32_bf16 v[86:89], v[134:137], v[188:191], v[86:89]
	v_mfma_f32_16x16x32_bf16 v[82:85], v[142:145], v[188:191], v[82:85]
	s_barrier
	s_add_i32 s22, s38, s79
	v_add_u32_e32 v204, s35, v217
	s_mov_b32 m0, s22
	ds_read_b128 v[192:195], v204
	ds_read_b128 v[196:199], v204 offset:1024
	ds_read_b128 v[200:203], v204 offset:2048
	ds_read_b128 v[204:207], v204 offset:3072
	global_load_lds_dwordx4 v164, s[98:99]
	s_add_i32 m0, s22, 0x2000
	s_nop 0
	global_load_lds_dwordx4 v170, s[98:99]
	s_add_u32 s98, s98, s94
	s_addc_u32 s99, s99, 0
	s_barrier
; #define PG8_STAGE(bufoff, gbase, voff) do { _Pragma("unroll") for (int _i = 0; _i < 2; ++_i) \
;         __builtin_amdgcn_global_load_lds((const unsigned*)((const char*)(gbase) + (voff)[_i]), (PG8_LAS unsigned*)(lds + (bufoff) + ldsw + _i * 8192), 16, 0, 0); } while (0)
; #define PG8_LDA(dst, b, h) do { _Pragma("unroll") for (int m = 0; m < 4; ++m) _Pragma("unroll") for (int k = 0; k < 2; ++k) dst[m][k] = *(const PG8_LAS bf16x8*)(lds + PG8_SA(b, h) + aoff + m * 2048 + k * 1024); } while (0)
; #define PG8_LDB(dst, b, h) do { _Pragma("unroll") for (int n = 0; n < 2; ++n) _Pragma("unroll") for (int k = 0; k < 2; ++k) dst[n][k] = *(const PG8_LAS bf16x8*)(lds + PG8_SB(b, h) + boff + n * 2048 + k * 1024); } while (0)
; #define PG8_MMA(ai, bj, At, Bt) do { __builtin_amdgcn_s_setprio(1); _Pragma("unroll") for (int m = 0; m < 4; ++m) _Pragma("unroll") for (int n = 0; n < 2; ++n) _Pragma("unroll") for (int k = 0; k < 2; ++k) \
;         acc[ai][bj][m][n] = __builtin_amdgcn_mfma_f32_16x16x32_bf16(Bt[n][k], At[m][k], acc[ai][bj][m][n], 0, 0, 0); __builtin_amdgcn_s_setprio(0); } while (0)
; #define PG8_WAIT_V(n) asm volatile("s_waitcnt vmcnt(" #n ")" ::: "memory")
; #define PG8_WAIT_L(n) asm volatile("s_waitcnt lgkmcnt(" #n ")" ::: "memory")
; #define PG8_BAR __builtin_amdgcn_s_barrier()
; #define PG8_SCHED __builtin_amdgcn_sched_barrier(0)
; template <class Epi, class Sched, bool STAMP = false>
; __device__ __forceinline__ void gemm_phase(PG8_LAS unsigned char* lds, const Gemm g, const Sched& S, const Epi& E, unsigned long long* stamps) {
;     ...
;             PG8_LDB(B1, 1, 1); PG8_STAGE(PG8_SB(1, 0), b3, voffB);
;             PG8_BAR; PG8_WAIT_L(0); PG8_MMA(0, 1, At, B1); PG8_BAR;
;             PG8_LDA(At, 1, 1); PG8_STAGE(PG8_SA(1, 0), a3, voffA);
;             PG8_BAR; PG8_WAIT_L(0); PG8_MMA(1, 0, At, B0); PG8_BAR; PG8_SCHED;
;             PG8_STAGE(PG8_SB(1, 1), b3 + hstep, voffB);
;             PG8_WAIT_V(6); PG8_BAR; PG8_MMA(1, 1, At, B1); PG8_BAR;
;         }
	s_waitcnt lgkmcnt(0)
	s_waitcnt lgkmcnt(0)
	v_mfma_f32_16x16x32_bf16 v[110:113], v[192:195], v[146:149], v[110:113]
	v_mfma_f32_16x16x32_bf16 v[106:109], v[200:203], v[146:149], v[106:109]
	v_mfma_f32_16x16x32_bf16 v[94:97], v[192:195], v[154:157], v[94:97]
	v_mfma_f32_16x16x32_bf16 v[90:93], v[200:203], v[154:157], v[90:93]
	v_mfma_f32_16x16x32_bf16 v[78:81], v[192:195], v[176:179], v[78:81]
	v_mfma_f32_16x16x32_bf16 v[74:77], v[200:203], v[176:179], v[74:77]
	v_mfma_f32_16x16x32_bf16 v[70:73], v[192:195], v[184:187], v[70:73]
	v_mfma_f32_16x16x32_bf16 v[66:69], v[200:203], v[184:187], v[66:69]
	v_mfma_f32_16x16x32_bf16 v[110:113], v[196:199], v[150:153], v[110:113]
	v_mfma_f32_16x16x32_bf16 v[106:109], v[204:207], v[150:153], v[106:109]
	v_mfma_f32_16x16x32_bf16 v[94:97], v[196:199], v[158:161], v[94:97]
	v_mfma_f32_16x16x32_bf16 v[90:93], v[204:207], v[158:161], v[90:93]
	v_mfma_f32_16x16x32_bf16 v[78:81], v[196:199], v[180:183], v[78:81]
	v_mfma_f32_16x16x32_bf16 v[74:77], v[204:207], v[180:183], v[74:77]
	v_mfma_f32_16x16x32_bf16 v[70:73], v[196:199], v[188:191], v[70:73]
	v_mfma_f32_16x16x32_bf16 v[66:69], v[204:207], v[188:191], v[66:69]
	s_mov_b32 m0, s33
	s_barrier
	ds_read_b128 v[146:149], v218 offset:49152
	ds_read_b128 v[150:153], v218 offset:50176
	ds_read_b128 v[154:157], v218 offset:51200
	ds_read_b128 v[158:161], v218 offset:52224
	ds_read_b128 v[176:179], v218 offset:53248
	ds_read_b128 v[180:183], v218 offset:54272
	ds_read_b128 v[184:187], v218 offset:55296
	ds_read_b128 v[188:191], v218 offset:56320
	global_load_lds_dwordx4 v162, s[100:101]
	s_mov_b32 m0, s28
	s_nop 0
	global_load_lds_dwordx4 v166, s[100:101]
	s_barrier
	s_waitcnt lgkmcnt(0)
	s_waitcnt lgkmcnt(0)
	v_mfma_f32_16x16x32_bf16 v[62:65], v[130:133], v[146:149], v[62:65]
	v_mfma_f32_16x16x32_bf16 v[58:61], v[138:141], v[146:149], v[58:61]
	v_mfma_f32_16x16x32_bf16 v[54:57], v[130:133], v[154:157], v[54:57]
	v_mfma_f32_16x16x32_bf16 v[50:53], v[138:141], v[154:157], v[50:53]
	v_mfma_f32_16x16x32_bf16 v[38:41], v[130:133], v[176:179], v[38:41]
	v_mfma_f32_16x16x32_bf16 v[34:37], v[138:141], v[176:179], v[34:37]
	v_mfma_f32_16x16x32_bf16 v[22:25], v[130:133], v[184:187], v[22:25]
	v_mfma_f32_16x16x32_bf16 v[18:21], v[138:141], v[184:187], v[18:21]
	v_mfma_f32_16x16x32_bf16 v[62:65], v[134:137], v[150:153], v[62:65]
	v_mfma_f32_16x16x32_bf16 v[58:61], v[142:145], v[150:153], v[58:61]
	v_mfma_f32_16x16x32_bf16 v[54:57], v[134:137], v[158:161], v[54:57]
	v_mfma_f32_16x16x32_bf16 v[50:53], v[142:145], v[158:161], v[50:53]
	v_mfma_f32_16x16x32_bf16 v[38:41], v[134:137], v[180:183], v[38:41]
	v_mfma_f32_16x16x32_bf16 v[34:37], v[142:145], v[180:183], v[34:37]
	v_mfma_f32_16x16x32_bf16 v[22:25], v[134:137], v[188:191], v[22:25]
	v_mfma_f32_16x16x32_bf16 v[18:21], v[142:145], v[188:191], v[18:21]
	s_barrier
	s_add_i32 s22, s35, s79
	s_mov_b32 m0, s22
	s_nop 0
	global_load_lds_dwordx4 v164, s[98:99]
	s_add_i32 m0, s22, 0x2000
	s_nop 0
	global_load_lds_dwordx4 v170, s[98:99]
	s_waitcnt vmcnt(6)
	s_barrier
	v_mfma_f32_16x16x32_bf16 v[46:49], v[192:195], v[146:149], v[46:49]
	v_mfma_f32_16x16x32_bf16 v[42:45], v[200:203], v[146:149], v[42:45]
	v_mfma_f32_16x16x32_bf16 v[30:33], v[192:195], v[154:157], v[30:33]
	v_mfma_f32_16x16x32_bf16 v[26:29], v[200:203], v[154:157], v[26:29]
	v_mfma_f32_16x16x32_bf16 v[14:17], v[192:195], v[176:179], v[14:17]
	v_mfma_f32_16x16x32_bf16 v[10:13], v[200:203], v[176:179], v[10:13]
	v_mfma_f32_16x16x32_bf16 v[6:9], v[192:195], v[184:187], v[6:9]
	v_mfma_f32_16x16x32_bf16 v[2:5], v[200:203], v[184:187], v[2:5]
	v_mfma_f32_16x16x32_bf16 v[46:49], v[196:199], v[150:153], v[46:49]
	v_mfma_f32_16x16x32_bf16 v[42:45], v[204:207], v[150:153], v[42:45]
	v_mfma_f32_16x16x32_bf16 v[30:33], v[196:199], v[158:161], v[30:33]
	v_mfma_f32_16x16x32_bf16 v[26:29], v[204:207], v[158:161], v[26:29]
	v_mfma_f32_16x16x32_bf16 v[14:17], v[196:199], v[180:183], v[14:17]
	v_mfma_f32_16x16x32_bf16 v[10:13], v[204:207], v[180:183], v[10:13]
	v_mfma_f32_16x16x32_bf16 v[6:9], v[196:199], v[188:191], v[6:9]
	v_mfma_f32_16x16x32_bf16 v[2:5], v[204:207], v[188:191], v[2:5]
	s_add_u32 s0, s0, 0x100
	s_addc_u32 s1, s1, 0
	s_add_u32 s88, s88, 0x100
	s_addc_u32 s89, s89, 0
	s_cmp_ge_u32 s93, s26
	s_mov_b32 s22, s93
	s_barrier
	s_cbranch_scc0 .LBB0_745
	s_branch .Lg_epi

; DI float lo2f(unsigned u) { return __uint_as_float(u << 16); }
; DI float hi2f(unsigned u) { return __uint_as_float(u & 0xffff0000u); }
; DI float sigmoidf_(float x) { return __builtin_amdgcn_rcpf(1.f + __builtin_amdgcn_exp2f(-1.4426950408889634f * x)); }
;   DI void operator()(const f32x4 (&acc)[2][2][4][2], const pg8::Unit& u, int wr, int wc, int fr, int fq) const {
;     ...
;     } else {
; #pragma unroll
;       for (int ai = 0; ai < 2; ++ai) {
;         uint4 gs[4][2];
; #pragma unroll
;         for (int m = 0; m < 4; ++m)
; #pragma unroll
;           for (int bj = 0; bj < 2; ++bj)
;             gs[m][bj] = *(const uint4*)(o0 + (size_t)(row0 + ai * 128 + m * 16) * DFF + col0 + bj * 128);
;         __builtin_amdgcn_sched_barrier(0);
; #pragma unroll
;         for (int m = 0; m < 4; ++m)
; #pragma unroll
;           for (int bj = 0; bj < 2; ++bj) {
;             const f32x4 v0 = acc[ai][bj][m][0], v1 = acc[ai][bj][m][1];
;             const uint4 g = gs[m][bj];
;             f32x4 q0 = {lo2f(g.x) * v0[0], hi2f(g.x) * v0[1], lo2f(g.y) * v0[2], hi2f(g.y) * v0[3]};
;             f32x4 q1 = {lo2f(g.z) * v1[0], hi2f(g.z) * v1[1], lo2f(g.w) * v1[2], hi2f(g.w) * v1[3]};
;             st8(o0 + (size_t)(row0 + ai * 128 + m * 16) * DFF + col0 + bj * 128, q0, q1);
; DI void conv_phase(const Params& p, int l) {
;     ...
;     const int rr = it / (DFF / 8), cg = it - rr * (DFF / 8);
;     const int t0 = rr * RUN, c0 = cg * 8;
;     const u16* gp = G + (size_t)t0 * DFF + c0;
;     const int s0 = t0 & (S - 1);
;     uint4 rows[RUN + 2];
;     const uint4 z = make_uint4(0, 0, 0, 0);
;     rows[0] = (s0 > 0) ? *(const uint4*)(gp - DFF) : z;
; #pragma unroll
;     for (int i = 0; i < RUN; ++i) rows[i + 1] = *(const uint4*)(gp + (size_t)i * DFF);
;     rows[RUN + 1] = (s0 + RUN - 1 < S - 1) ? *(const uint4*)(gp + (size_t)RUN * DFF) : z;
;     float w0[8], w1[8], w2[8], bb[8];
;     load8f(cw + c0, w0); load8f(cw + DFF + c0, w1); load8f(cw + 2 * DFF + c0, w2); load8f(cb + c0, bb);
;     float prev[8], cur[8], nxt[8];
;     unpack8(rows[0], prev); unpack8(rows[1], cur);
; #pragma unroll
;     for (int i = 0; i < RUN; ++i) {
;       unpack8(rows[i + 2], nxt);
;       float o[8];
; #pragma unroll
;       for (int j = 0; j < 8; ++j) { const float g = w0[j] * prev[j] + w1[j] * cur[j] + w2[j] * nxt[j] + bb[j]; o[j] = g * sigmoidf_(g); }
.Lg_epi:
	s_lshl_b32 s22, s75, 8
	s_lshl_b32 s0, s97, 8
	s_add_i32 s22, s22, s5
	s_or_b32 s75, s0, s72
	v_or_b32_e32 v176, s22, v1
	v_or_b32_e32 v178, s75, v216
	s_cmp_lt_i32 s77, 2
	s_mov_b64 s[0:1], -1
	s_cbranch_scc1 .LBB0_752
	s_cmp_gt_i32 s77, 2
	s_cbranch_scc0 .LBB0_749
	v_ashrrev_i32_e32 v179, 31, v178
	v_lshlrev_b64 v[180:181], 1, v[178:179]
	v_lshl_add_u64 v[180:181], s[46:47], 0, v[180:181]
	v_add_co_u32_e32 v180, vcc, 0xea000000, v180
	s_nop 1
	v_addc_co_u32_e32 v181, vcc, -1, v181, vcc
	v_lshlrev_b32_e32 v182, 2, v178
	v_readlane_b32 s98, v237, 62
	v_readlane_b32 s100, v238, 0
	v_readlane_b32 s101, v238, 1
	s_mul_i32 s98, s98, 0xab
	s_bfe_u32 s98, s98, 0x6000a
	s_mul_i32 s99, s98, 0x8400
	s_add_u32 s100, s100, s99
	s_addc_u32 s101, s101, 0
	s_nop 3
	global_load_dwordx4 v[130:133], v182, s[100:101] offset:0
	global_load_dwordx4 v[134:137], v182, s[100:101] offset:16
	s_add_u32 s100, s100, 0x2c00
	s_addc_u32 s101, s101, 0
	global_load_dwordx4 v[138:141], v182, s[100:101] offset:0
	global_load_dwordx4 v[142:145], v182, s[100:101] offset:16
	s_add_u32 s100, s100, 0x2c00
	s_addc_u32 s101, s101, 0
	global_load_dwordx4 v[146:149], v182, s[100:101] offset:0
	global_load_dwordx4 v[150:153], v182, s[100:101] offset:16
	v_readlane_b32 s100, v238, 2
	v_readlane_b32 s101, v238, 3
	s_mul_i32 s99, s98, 0x2c00
	s_add_u32 s100, s100, s99
	s_addc_u32 s101, s101, 0
	s_nop 3
	global_load_dwordx4 v[154:157], v182, s[100:101] offset:0
	global_load_dwordx4 v[158:161], v182, s[100:101] offset:16
	s_mov_b32 s98, 0x1600
	s_mov_b32 s99, 0
	s_mov_b32 s100, 0x16000000
	s_mov_b32 s101, 0
	v_add_u32_e32 v183, -1, v176
	v_mad_i64_i32 v[222:223], s[0:1], v183, s14, v[180:181]
	v_lshl_add_u64 v[224:225], v[222:223], 0, s[98:99]
	v_lshl_add_u64 v[226:227], v[224:225], 0, s[98:99]
	v_lshl_add_u64 v[196:197], v[224:225], 0, s[100:101]
	global_load_dwordx4 v[184:187], v[222:223], off
	global_load_dwordx4 v[188:191], v[224:225], off
	global_load_dwordx4 v[192:195], v[226:227], off
	v_add_u32_e32 v183, 0xf, v176
	v_mad_i64_i32 v[222:223], s[0:1], v183, s14, v[180:181]
	v_lshl_add_u64 v[224:225], v[222:223], 0, s[98:99]
	v_lshl_add_u64 v[226:227], v[224:225], 0, s[98:99]
	v_lshl_add_u64 v[220:221], v[224:225], 0, s[100:101]
	global_load_dwordx4 v[198:201], v[222:223], off
	global_load_dwordx4 v[202:205], v[224:225], off
	global_load_dwordx4 v[206:209], v[226:227], off
	s_waitcnt vmcnt(3)
	v_and_b32_e32 v183, 0x1fff, v176
	v_cmp_eq_u32_e32 vcc, 0, v183
	v_cndmask_b32_e64 v184, v184, 0, vcc
	v_cndmask_b32_e64 v185, v185, 0, vcc
	v_cndmask_b32_e64 v186, v186, 0, vcc
	v_cndmask_b32_e64 v187, v187, 0, vcc
	v_lshlrev_b32_e32 v240, 16, v184
	v_and_b32_e32 v241, 0xffff0000, v184
	v_lshlrev_b32_e32 v242, 16, v188
	v_and_b32_e32 v243, 0xffff0000, v188
	v_lshlrev_b32_e32 v252, 16, v192
	v_and_b32_e32 v253, 0xffff0000, v192
	v_fma_f32 v254, v130, v240, v154
	v_fma_f32 v255, v131, v241, v155
	v_fma_f32 v254, v138, v242, v254
	v_fma_f32 v255, v139, v243, v255
	v_fma_f32 v254, v146, v252, v254
	v_fma_f32 v255, v147, v253, v255
	v_mul_f32_e32 v240, 0xbfb8aa3b, v254
	v_mul_f32_e32 v241, 0xbfb8aa3b, v255
	v_exp_f32_e32 v240, v240
	v_exp_f32_e32 v241, v241
	v_add_f32_e32 v240, 1.0, v240
	v_add_f32_e32 v241, 1.0, v241
	v_rcp_f32_e32 v240, v240
	v_rcp_f32_e32 v241, v241
	v_mul_f32_e32 v254, v254, v240
	v_mul_f32_e32 v255, v255, v241
	v_mul_f32_e32 v254, v254, v126
	v_mul_f32_e32 v255, v255, v127
	v_cvt_pk_bf16_f32 v244, v254, v255
	v_lshlrev_b32_e32 v240, 16, v185
	v_and_b32_e32 v241, 0xffff0000, v185
	v_lshlrev_b32_e32 v242, 16, v189
	v_and_b32_e32 v243, 0xffff0000, v189
	v_lshlrev_b32_e32 v252, 16, v193
	v_and_b32_e32 v253, 0xffff0000, v193
	v_fma_f32 v254, v132, v240, v156
	v_fma_f32 v255, v133, v241, v157
	v_fma_f32 v254, v140, v242, v254
	v_fma_f32 v255, v141, v243, v255
	v_fma_f32 v254, v148, v252, v254
	v_fma_f32 v255, v149, v253, v255
	v_mul_f32_e32 v240, 0xbfb8aa3b, v254
	v_mul_f32_e32 v241, 0xbfb8aa3b, v255
	v_exp_f32_e32 v240, v240
	v_exp_f32_e32 v241, v241
	v_add_f32_e32 v240, 1.0, v240
	v_add_f32_e32 v241, 1.0, v241
	v_rcp_f32_e32 v240, v240
	v_rcp_f32_e32 v241, v241
	v_mul_f32_e32 v254, v254, v240
	v_mul_f32_e32 v255, v255, v241
	v_mul_f32_e32 v254, v254, v128
	v_mul_f32_e32 v255, v255, v129
	v_cvt_pk_bf16_f32 v245, v254, v255
	v_lshlrev_b32_e32 v240, 16, v186
	v_and_b32_e32 v241, 0xffff0000, v186
	v_lshlrev_b32_e32 v242, 16, v190
	v_and_b32_e32 v243, 0xffff0000, v190
	v_lshlrev_b32_e32 v252, 16, v194
	v_and_b32_e32 v253, 0xffff0000, v194
	v_fma_f32 v254, v134, v240, v158
	v_fma_f32 v255, v135, v241, v159
	v_fma_f32 v254, v142, v242, v254
	v_fma_f32 v255, v143, v243, v255
	v_fma_f32 v254, v150, v252, v254
	v_fma_f32 v255, v151, v253, v255
	v_mul_f32_e32 v240, 0xbfb8aa3b, v254
	v_mul_f32_e32 v241, 0xbfb8aa3b, v255
	v_exp_f32_e32 v240, v240
	v_exp_f32_e32 v241, v241
	v_add_f32_e32 v240, 1.0, v240
	v_add_f32_e32 v241, 1.0, v241
	v_rcp_f32_e32 v240, v240
	v_rcp_f32_e32 v241, v241
	v_mul_f32_e32 v254, v254, v240
	v_mul_f32_e32 v255, v255, v241
	v_mul_f32_e32 v254, v254, v122
	v_mul_f32_e32 v255, v255, v123
	v_cvt_pk_bf16_f32 v246, v254, v255
	v_lshlrev_b32_e32 v240, 16, v187
	v_and_b32_e32 v241, 0xffff0000, v187
	v_lshlrev_b32_e32 v242, 16, v191
	v_and_b32_e32 v243, 0xffff0000, v191
	v_lshlrev_b32_e32 v252, 16, v195
	v_and_b32_e32 v253, 0xffff0000, v195
	v_fma_f32 v254, v136, v240, v160
	v_fma_f32 v255, v137, v241, v161
	v_fma_f32 v254, v144, v242, v254
	v_fma_f32 v255, v145, v243, v255
	v_fma_f32 v254, v152, v252, v254
	v_fma_f32 v255, v153, v253, v255
	v_mul_f32_e32 v240, 0xbfb8aa3b, v254
	v_mul_f32_e32 v241, 0xbfb8aa3b, v255
	v_exp_f32_e32 v240, v240
	v_exp_f32_e32 v241, v241
	v_add_f32_e32 v240, 1.0, v240
	v_add_f32_e32 v241, 1.0, v241
	v_rcp_f32_e32 v240, v240
	v_rcp_f32_e32 v241, v241
	v_mul_f32_e32 v254, v254, v240
	v_mul_f32_e32 v255, v255, v241
	v_mul_f32_e32 v254, v254, v124
	v_mul_f32_e32 v255, v255, v125
	v_cvt_pk_bf16_f32 v247, v254, v255
	global_store_dwordx4 v[196:197], v[244:247], off
	v_add_u32_e32 v183, 0x1f, v176
	v_mad_i64_i32 v[222:223], s[0:1], v183, s14, v[180:181]
	v_lshl_add_u64 v[224:225], v[222:223], 0, s[98:99]
	v_lshl_add_u64 v[226:227], v[224:225], 0, s[98:99]
	v_lshl_add_u64 v[196:197], v[224:225], 0, s[100:101]
	global_load_dwordx4 v[184:187], v[222:223], off
	global_load_dwordx4 v[188:191], v[224:225], off
	global_load_dwordx4 v[192:195], v[226:227], off
	s_waitcnt vmcnt(4)
; DI unsigned pack2(float a, float b) { f32x2_t v = {a, b}; bf16x2_t r = __builtin_convertvector(v, bf16x2_t); return __builtin_bit_cast(unsigned, r); }
; DI float lo2f(unsigned u) { return __uint_as_float(u << 16); }
; DI float hi2f(unsigned u) { return __uint_as_float(u & 0xffff0000u); }
; DI float sigmoidf_(float x) { return __builtin_amdgcn_rcpf(1.f + __builtin_amdgcn_exp2f(-1.4426950408889634f * x)); }
;   DI void operator()(const f32x4 (&acc)[2][2][4][2], const pg8::Unit& u, int wr, int wc, int fr, int fq) const {
;     ...
;           for (int bj = 0; bj < 2; ++bj) {
;             const f32x4 v0 = acc[ai][bj][m][0], v1 = acc[ai][bj][m][1];
;             const uint4 g = gs[m][bj];
;             f32x4 q0 = {lo2f(g.x) * v0[0], hi2f(g.x) * v0[1], lo2f(g.y) * v0[2], hi2f(g.y) * v0[3]};
;             f32x4 q1 = {lo2f(g.z) * v1[0], hi2f(g.z) * v1[1], lo2f(g.w) * v1[2], hi2f(g.w) * v1[3]};
;             st8(o0 + (size_t)(row0 + ai * 128 + m * 16) * DFF + col0 + bj * 128, q0, q1);
; DI void conv_phase(const Params& p, int l) {
;     ...
;     for (int i = 0; i < RUN; ++i) {
;       unpack8(rows[i + 2], nxt);
;       float o[8];
; #pragma unroll
;       for (int j = 0; j < 8; ++j) { const float g = w0[j] * prev[j] + w1[j] * cur[j] + w2[j] * nxt[j] + bb[j]; o[j] = g * sigmoidf_(g); }
;       uint4 oo; oo.x = pack2(o[0], o[1]); oo.y = pack2(o[2], o[3]); oo.z = pack2(o[4], o[5]); oo.w = pack2(o[6], o[7]);
;       *(uint4*)(GS + (size_t)(t0 + i) * DFF + c0) = oo;
	v_lshlrev_b32_e32 v240, 16, v198
	v_and_b32_e32 v241, 0xffff0000, v198
	v_lshlrev_b32_e32 v242, 16, v202
	v_and_b32_e32 v243, 0xffff0000, v202
	v_lshlrev_b32_e32 v252, 16, v206
	v_and_b32_e32 v253, 0xffff0000, v206
	v_fma_f32 v254, v130, v240, v154
	v_fma_f32 v255, v131, v241, v155
	v_fma_f32 v254, v138, v242, v254
	v_fma_f32 v255, v139, v243, v255
	v_fma_f32 v254, v146, v252, v254
	v_fma_f32 v255, v147, v253, v255
	v_mul_f32_e32 v240, 0xbfb8aa3b, v254
	v_mul_f32_e32 v241, 0xbfb8aa3b, v255
	v_exp_f32_e32 v240, v240
	v_exp_f32_e32 v241, v241
	v_add_f32_e32 v240, 1.0, v240
	v_add_f32_e32 v241, 1.0, v241
	v_rcp_f32_e32 v240, v240
	v_rcp_f32_e32 v241, v241
	v_mul_f32_e32 v254, v254, v240
	v_mul_f32_e32 v255, v255, v241
	v_mul_f32_e32 v254, v254, v118
	v_mul_f32_e32 v255, v255, v119
	v_cvt_pk_bf16_f32 v248, v254, v255
	v_lshlrev_b32_e32 v240, 16, v199
	v_and_b32_e32 v241, 0xffff0000, v199
	v_lshlrev_b32_e32 v242, 16, v203
	v_and_b32_e32 v243, 0xffff0000, v203
	v_lshlrev_b32_e32 v252, 16, v207
	v_and_b32_e32 v253, 0xffff0000, v207
	v_fma_f32 v254, v132, v240, v156
	v_fma_f32 v255, v133, v241, v157
	v_fma_f32 v254, v140, v242, v254
	v_fma_f32 v255, v141, v243, v255
	v_fma_f32 v254, v148, v252, v254
	v_fma_f32 v255, v149, v253, v255
	v_mul_f32_e32 v240, 0xbfb8aa3b, v254
	v_mul_f32_e32 v241, 0xbfb8aa3b, v255
	v_exp_f32_e32 v240, v240
	v_exp_f32_e32 v241, v241
	v_add_f32_e32 v240, 1.0, v240
	v_add_f32_e32 v241, 1.0, v241
	v_rcp_f32_e32 v240, v240
	v_rcp_f32_e32 v241, v241
	v_mul_f32_e32 v254, v254, v240
	v_mul_f32_e32 v255, v255, v241
	v_mul_f32_e32 v254, v254, v120
	v_mul_f32_e32 v255, v255, v121
	v_cvt_pk_bf16_f32 v249, v254, v255
	v_lshlrev_b32_e32 v240, 16, v200
	v_and_b32_e32 v241, 0xffff0000, v200
	v_lshlrev_b32_e32 v242, 16, v204
	v_and_b32_e32 v243, 0xffff0000, v204
	v_lshlrev_b32_e32 v252, 16, v208
	v_and_b32_e32 v253, 0xffff0000, v208
	v_fma_f32 v254, v134, v240, v158
	v_fma_f32 v255, v135, v241, v159
	v_fma_f32 v254, v142, v242, v254
	v_fma_f32 v255, v143, v243, v255
	v_fma_f32 v254, v150, v252, v254
	v_fma_f32 v255, v151, v253, v255
	v_mul_f32_e32 v240, 0xbfb8aa3b, v254
	v_mul_f32_e32 v241, 0xbfb8aa3b, v255
	v_exp_f32_e32 v240, v240
	v_exp_f32_e32 v241, v241
	v_add_f32_e32 v240, 1.0, v240
	v_add_f32_e32 v241, 1.0, v241
	v_rcp_f32_e32 v240, v240
	v_rcp_f32_e32 v241, v241
	v_mul_f32_e32 v254, v254, v240
	v_mul_f32_e32 v255, v255, v241
	v_mul_f32_e32 v254, v254, v114
	v_mul_f32_e32 v255, v255, v115
	v_cvt_pk_bf16_f32 v250, v254, v255
	v_lshlrev_b32_e32 v240, 16, v201
	v_and_b32_e32 v241, 0xffff0000, v201
	v_lshlrev_b32_e32 v242, 16, v205
	v_and_b32_e32 v243, 0xffff0000, v205
	v_lshlrev_b32_e32 v252, 16, v209
	v_and_b32_e32 v253, 0xffff0000, v209
	v_fma_f32 v254, v136, v240, v160
	v_fma_f32 v255, v137, v241, v161
	v_fma_f32 v254, v144, v242, v254
	v_fma_f32 v255, v145, v243, v255
	v_fma_f32 v254, v152, v252, v254
	v_fma_f32 v255, v153, v253, v255
	v_mul_f32_e32 v240, 0xbfb8aa3b, v254
	v_mul_f32_e32 v241, 0xbfb8aa3b, v255
	v_exp_f32_e32 v240, v240
	v_exp_f32_e32 v241, v241
	v_add_f32_e32 v240, 1.0, v240
	v_add_f32_e32 v241, 1.0, v241
	v_rcp_f32_e32 v240, v240
	v_rcp_f32_e32 v241, v241
	v_mul_f32_e32 v254, v254, v240
	v_mul_f32_e32 v255, v255, v241
	v_mul_f32_e32 v254, v254, v116
	v_mul_f32_e32 v255, v255, v117
	v_cvt_pk_bf16_f32 v251, v254, v255
	global_store_dwordx4 v[220:221], v[248:251], off
	v_add_u32_e32 v183, 0x2f, v176
	v_mad_i64_i32 v[222:223], s[0:1], v183, s14, v[180:181]
	v_lshl_add_u64 v[224:225], v[222:223], 0, s[98:99]
	v_lshl_add_u64 v[226:227], v[224:225], 0, s[98:99]
	v_lshl_add_u64 v[220:221], v[224:225], 0, s[100:101]
	global_load_dwordx4 v[198:201], v[222:223], off
	global_load_dwordx4 v[202:205], v[224:225], off
	global_load_dwordx4 v[206:209], v[226:227], off
	s_waitcnt vmcnt(4)
	v_lshlrev_b32_e32 v240, 16, v184
	v_and_b32_e32 v241, 0xffff0000, v184
	v_lshlrev_b32_e32 v242, 16, v188
	v_and_b32_e32 v243, 0xffff0000, v188
	v_lshlrev_b32_e32 v252, 16, v192
	v_and_b32_e32 v253, 0xffff0000, v192
	v_fma_f32 v254, v130, v240, v154
	v_fma_f32 v255, v131, v241, v155
	v_fma_f32 v254, v138, v242, v254
	v_fma_f32 v255, v139, v243, v255
	v_fma_f32 v254, v146, v252, v254
	v_fma_f32 v255, v147, v253, v255
	v_mul_f32_e32 v240, 0xbfb8aa3b, v254
	v_mul_f32_e32 v241, 0xbfb8aa3b, v255
	v_exp_f32_e32 v240, v240
	v_exp_f32_e32 v241, v241
	v_add_f32_e32 v240, 1.0, v240
	v_add_f32_e32 v241, 1.0, v241
	v_rcp_f32_e32 v240, v240
	v_rcp_f32_e32 v241, v241
	v_mul_f32_e32 v254, v254, v240
	v_mul_f32_e32 v255, v255, v241
	v_mul_f32_e32 v254, v254, v102
	v_mul_f32_e32 v255, v255, v103
	v_cvt_pk_bf16_f32 v244, v254, v255
	v_lshlrev_b32_e32 v240, 16, v185
	v_and_b32_e32 v241, 0xffff0000, v185
	v_lshlrev_b32_e32 v242, 16, v189
	v_and_b32_e32 v243, 0xffff0000, v189
	v_lshlrev_b32_e32 v252, 16, v193
	v_and_b32_e32 v253, 0xffff0000, v193
	v_fma_f32 v254, v132, v240, v156
	v_fma_f32 v255, v133, v241, v157
	v_fma_f32 v254, v140, v242, v254
	v_fma_f32 v255, v141, v243, v255
	v_fma_f32 v254, v148, v252, v254
	v_fma_f32 v255, v149, v253, v255
	v_mul_f32_e32 v240, 0xbfb8aa3b, v254
	v_mul_f32_e32 v241, 0xbfb8aa3b, v255
	v_exp_f32_e32 v240, v240
	v_exp_f32_e32 v241, v241
	v_add_f32_e32 v240, 1.0, v240
	v_add_f32_e32 v241, 1.0, v241
	v_rcp_f32_e32 v240, v240
	v_rcp_f32_e32 v241, v241
	v_mul_f32_e32 v254, v254, v240
	v_mul_f32_e32 v255, v255, v241
	v_mul_f32_e32 v254, v254, v104
	v_mul_f32_e32 v255, v255, v105
	v_cvt_pk_bf16_f32 v245, v254, v255
	v_lshlrev_b32_e32 v240, 16, v186
	v_and_b32_e32 v241, 0xffff0000, v186
	v_lshlrev_b32_e32 v242, 16, v190
	v_and_b32_e32 v243, 0xffff0000, v190
	v_lshlrev_b32_e32 v252, 16, v194
	v_and_b32_e32 v253, 0xffff0000, v194
; DI unsigned pack2(float a, float b) { f32x2_t v = {a, b}; bf16x2_t r = __builtin_convertvector(v, bf16x2_t); return __builtin_bit_cast(unsigned, r); }
; DI float lo2f(unsigned u) { return __uint_as_float(u << 16); }
; DI float hi2f(unsigned u) { return __uint_as_float(u & 0xffff0000u); }
; DI float sigmoidf_(float x) { return __builtin_amdgcn_rcpf(1.f + __builtin_amdgcn_exp2f(-1.4426950408889634f * x)); }
;   DI void operator()(const f32x4 (&acc)[2][2][4][2], const pg8::Unit& u, int wr, int wc, int fr, int fq) const {
;     ...
;           for (int bj = 0; bj < 2; ++bj) {
;             const f32x4 v0 = acc[ai][bj][m][0], v1 = acc[ai][bj][m][1];
;             const uint4 g = gs[m][bj];
;             f32x4 q0 = {lo2f(g.x) * v0[0], hi2f(g.x) * v0[1], lo2f(g.y) * v0[2], hi2f(g.y) * v0[3]};
;             f32x4 q1 = {lo2f(g.z) * v1[0], hi2f(g.z) * v1[1], lo2f(g.w) * v1[2], hi2f(g.w) * v1[3]};
;             st8(o0 + (size_t)(row0 + ai * 128 + m * 16) * DFF + col0 + bj * 128, q0, q1);
; DI void conv_phase(const Params& p, int l) {
;     ...
;     for (int i = 0; i < RUN; ++i) {
;       unpack8(rows[i + 2], nxt);
;       float o[8];
; #pragma unroll
;       for (int j = 0; j < 8; ++j) { const float g = w0[j] * prev[j] + w1[j] * cur[j] + w2[j] * nxt[j] + bb[j]; o[j] = g * sigmoidf_(g); }
;       uint4 oo; oo.x = pack2(o[0], o[1]); oo.y = pack2(o[2], o[3]); oo.z = pack2(o[4], o[5]); oo.w = pack2(o[6], o[7]);
;       *(uint4*)(GS + (size_t)(t0 + i) * DFF + c0) = oo;
	v_fma_f32 v254, v134, v240, v158
	v_fma_f32 v255, v135, v241, v159
	v_fma_f32 v254, v142, v242, v254
	v_fma_f32 v255, v143, v243, v255
	v_fma_f32 v254, v150, v252, v254
	v_fma_f32 v255, v151, v253, v255
	v_mul_f32_e32 v240, 0xbfb8aa3b, v254
	v_mul_f32_e32 v241, 0xbfb8aa3b, v255
	v_exp_f32_e32 v240, v240
	v_exp_f32_e32 v241, v241
	v_add_f32_e32 v240, 1.0, v240
	v_add_f32_e32 v241, 1.0, v241
	v_rcp_f32_e32 v240, v240
	v_rcp_f32_e32 v241, v241
	v_mul_f32_e32 v254, v254, v240
	v_mul_f32_e32 v255, v255, v241
	v_mul_f32_e32 v254, v254, v98
	v_mul_f32_e32 v255, v255, v99
	v_cvt_pk_bf16_f32 v246, v254, v255
	v_lshlrev_b32_e32 v240, 16, v187
	v_and_b32_e32 v241, 0xffff0000, v187
	v_lshlrev_b32_e32 v242, 16, v191
	v_and_b32_e32 v243, 0xffff0000, v191
	v_lshlrev_b32_e32 v252, 16, v195
	v_and_b32_e32 v253, 0xffff0000, v195
	v_fma_f32 v254, v136, v240, v160
	v_fma_f32 v255, v137, v241, v161
	v_fma_f32 v254, v144, v242, v254
	v_fma_f32 v255, v145, v243, v255
	v_fma_f32 v254, v152, v252, v254
	v_fma_f32 v255, v153, v253, v255
	v_mul_f32_e32 v240, 0xbfb8aa3b, v254
	v_mul_f32_e32 v241, 0xbfb8aa3b, v255
	v_exp_f32_e32 v240, v240
	v_exp_f32_e32 v241, v241
	v_add_f32_e32 v240, 1.0, v240
	v_add_f32_e32 v241, 1.0, v241
	v_rcp_f32_e32 v240, v240
	v_rcp_f32_e32 v241, v241
	v_mul_f32_e32 v254, v254, v240
	v_mul_f32_e32 v255, v255, v241
	v_mul_f32_e32 v254, v254, v100
	v_mul_f32_e32 v255, v255, v101
	v_cvt_pk_bf16_f32 v247, v254, v255
	global_store_dwordx4 v[196:197], v[244:247], off
	v_add_u32_e32 v183, 0x7f, v176
	v_mad_i64_i32 v[222:223], s[0:1], v183, s14, v[180:181]
	v_lshl_add_u64 v[224:225], v[222:223], 0, s[98:99]
	v_lshl_add_u64 v[226:227], v[224:225], 0, s[98:99]
	v_lshl_add_u64 v[196:197], v[224:225], 0, s[100:101]
	global_load_dwordx4 v[184:187], v[222:223], off
	global_load_dwordx4 v[188:191], v[224:225], off
	global_load_dwordx4 v[192:195], v[226:227], off
	s_waitcnt vmcnt(4)
	v_lshlrev_b32_e32 v240, 16, v198
	v_and_b32_e32 v241, 0xffff0000, v198
	v_lshlrev_b32_e32 v242, 16, v202
	v_and_b32_e32 v243, 0xffff0000, v202
	v_lshlrev_b32_e32 v252, 16, v206
	v_and_b32_e32 v253, 0xffff0000, v206
	v_fma_f32 v254, v130, v240, v154
	v_fma_f32 v255, v131, v241, v155
	v_fma_f32 v254, v138, v242, v254
	v_fma_f32 v255, v139, v243, v255
	v_fma_f32 v254, v146, v252, v254
	v_fma_f32 v255, v147, v253, v255
	v_mul_f32_e32 v240, 0xbfb8aa3b, v254
	v_mul_f32_e32 v241, 0xbfb8aa3b, v255
	v_exp_f32_e32 v240, v240
	v_exp_f32_e32 v241, v241
	v_add_f32_e32 v240, 1.0, v240
	v_add_f32_e32 v241, 1.0, v241
	v_rcp_f32_e32 v240, v240
	v_rcp_f32_e32 v241, v241
	v_mul_f32_e32 v254, v254, v240
	v_mul_f32_e32 v255, v255, v241
	v_mul_f32_e32 v254, v254, v86
	v_mul_f32_e32 v255, v255, v87
	v_cvt_pk_bf16_f32 v248, v254, v255
	v_lshlrev_b32_e32 v240, 16, v199
	v_and_b32_e32 v241, 0xffff0000, v199
	v_lshlrev_b32_e32 v242, 16, v203
	v_and_b32_e32 v243, 0xffff0000, v203
	v_lshlrev_b32_e32 v252, 16, v207
	v_and_b32_e32 v253, 0xffff0000, v207
	v_fma_f32 v254, v132, v240, v156
	v_fma_f32 v255, v133, v241, v157
	v_fma_f32 v254, v140, v242, v254
	v_fma_f32 v255, v141, v243, v255
	v_fma_f32 v254, v148, v252, v254
	v_fma_f32 v255, v149, v253, v255
	v_mul_f32_e32 v240, 0xbfb8aa3b, v254
	v_mul_f32_e32 v241, 0xbfb8aa3b, v255
	v_exp_f32_e32 v240, v240
	v_exp_f32_e32 v241, v241
	v_add_f32_e32 v240, 1.0, v240
	v_add_f32_e32 v241, 1.0, v241
	v_rcp_f32_e32 v240, v240
	v_rcp_f32_e32 v241, v241
	v_mul_f32_e32 v254, v254, v240
	v_mul_f32_e32 v255, v255, v241
	v_mul_f32_e32 v254, v254, v88
	v_mul_f32_e32 v255, v255, v89
	v_cvt_pk_bf16_f32 v249, v254, v255
	v_lshlrev_b32_e32 v240, 16, v200
	v_and_b32_e32 v241, 0xffff0000, v200
	v_lshlrev_b32_e32 v242, 16, v204
	v_and_b32_e32 v243, 0xffff0000, v204
	v_lshlrev_b32_e32 v252, 16, v208
	v_and_b32_e32 v253, 0xffff0000, v208
	v_fma_f32 v254, v134, v240, v158
	v_fma_f32 v255, v135, v241, v159
	v_fma_f32 v254, v142, v242, v254
	v_fma_f32 v255, v143, v243, v255
	v_fma_f32 v254, v150, v252, v254
	v_fma_f32 v255, v151, v253, v255
	v_mul_f32_e32 v240, 0xbfb8aa3b, v254
	v_mul_f32_e32 v241, 0xbfb8aa3b, v255
	v_exp_f32_e32 v240, v240
	v_exp_f32_e32 v241, v241
	v_add_f32_e32 v240, 1.0, v240
	v_add_f32_e32 v241, 1.0, v241
	v_rcp_f32_e32 v240, v240
	v_rcp_f32_e32 v241, v241
	v_mul_f32_e32 v254, v254, v240
	v_mul_f32_e32 v255, v255, v241
	v_mul_f32_e32 v254, v254, v82
	v_mul_f32_e32 v255, v255, v83
	v_cvt_pk_bf16_f32 v250, v254, v255
	v_lshlrev_b32_e32 v240, 16, v201
	v_and_b32_e32 v241, 0xffff0000, v201
	v_lshlrev_b32_e32 v242, 16, v205
	v_and_b32_e32 v243, 0xffff0000, v205
	v_lshlrev_b32_e32 v252, 16, v209
	v_and_b32_e32 v253, 0xffff0000, v209
	v_fma_f32 v254, v136, v240, v160
	v_fma_f32 v255, v137, v241, v161
	v_fma_f32 v254, v144, v242, v254
	v_fma_f32 v255, v145, v243, v255
	v_fma_f32 v254, v152, v252, v254
	v_fma_f32 v255, v153, v253, v255
	v_mul_f32_e32 v240, 0xbfb8aa3b, v254
	v_mul_f32_e32 v241, 0xbfb8aa3b, v255
	v_exp_f32_e32 v240, v240
	v_exp_f32_e32 v241, v241
	v_add_f32_e32 v240, 1.0, v240
	v_add_f32_e32 v241, 1.0, v241
	v_rcp_f32_e32 v240, v240
	v_rcp_f32_e32 v241, v241
	v_mul_f32_e32 v254, v254, v240
	v_mul_f32_e32 v255, v255, v241
	v_mul_f32_e32 v254, v254, v84
	v_mul_f32_e32 v255, v255, v85
	v_cvt_pk_bf16_f32 v251, v254, v255
	global_store_dwordx4 v[220:221], v[248:251], off
	v_add_u32_e32 v183, 0x8f, v176
	v_mad_i64_i32 v[222:223], s[0:1], v183, s14, v[180:181]
	v_lshl_add_u64 v[224:225], v[222:223], 0, s[98:99]
	v_lshl_add_u64 v[226:227], v[224:225], 0, s[98:99]
	v_lshl_add_u64 v[220:221], v[224:225], 0, s[100:101]
	global_load_dwordx4 v[198:201], v[222:223], off
	global_load_dwordx4 v[202:205], v[224:225], off
	global_load_dwordx4 v[206:209], v[226:227], off
	s_waitcnt vmcnt(4)
; DI unsigned pack2(float a, float b) { f32x2_t v = {a, b}; bf16x2_t r = __builtin_convertvector(v, bf16x2_t); return __builtin_bit_cast(unsigned, r); }
; DI float lo2f(unsigned u) { return __uint_as_float(u << 16); }
; DI float hi2f(unsigned u) { return __uint_as_float(u & 0xffff0000u); }
; DI float sigmoidf_(float x) { return __builtin_amdgcn_rcpf(1.f + __builtin_amdgcn_exp2f(-1.4426950408889634f * x)); }
;   DI void operator()(const f32x4 (&acc)[2][2][4][2], const pg8::Unit& u, int wr, int wc, int fr, int fq) const {
;     ...
;           for (int bj = 0; bj < 2; ++bj) {
;             const f32x4 v0 = acc[ai][bj][m][0], v1 = acc[ai][bj][m][1];
;             const uint4 g = gs[m][bj];
;             f32x4 q0 = {lo2f(g.x) * v0[0], hi2f(g.x) * v0[1], lo2f(g.y) * v0[2], hi2f(g.y) * v0[3]};
;             f32x4 q1 = {lo2f(g.z) * v1[0], hi2f(g.z) * v1[1], lo2f(g.w) * v1[2], hi2f(g.w) * v1[3]};
;             st8(o0 + (size_t)(row0 + ai * 128 + m * 16) * DFF + col0 + bj * 128, q0, q1);
; DI void conv_phase(const Params& p, int l) {
;     ...
;     for (int i = 0; i < RUN; ++i) {
;       unpack8(rows[i + 2], nxt);
;       float o[8];
; #pragma unroll
;       for (int j = 0; j < 8; ++j) { const float g = w0[j] * prev[j] + w1[j] * cur[j] + w2[j] * nxt[j] + bb[j]; o[j] = g * sigmoidf_(g); }
;       uint4 oo; oo.x = pack2(o[0], o[1]); oo.y = pack2(o[2], o[3]); oo.z = pack2(o[4], o[5]); oo.w = pack2(o[6], o[7]);
;       *(uint4*)(GS + (size_t)(t0 + i) * DFF + c0) = oo;
	v_lshlrev_b32_e32 v240, 16, v184
	v_and_b32_e32 v241, 0xffff0000, v184
	v_lshlrev_b32_e32 v242, 16, v188
	v_and_b32_e32 v243, 0xffff0000, v188
	v_lshlrev_b32_e32 v252, 16, v192
	v_and_b32_e32 v253, 0xffff0000, v192
	v_fma_f32 v254, v130, v240, v154
	v_fma_f32 v255, v131, v241, v155
	v_fma_f32 v254, v138, v242, v254
	v_fma_f32 v255, v139, v243, v255
	v_fma_f32 v254, v146, v252, v254
	v_fma_f32 v255, v147, v253, v255
	v_mul_f32_e32 v240, 0xbfb8aa3b, v254
	v_mul_f32_e32 v241, 0xbfb8aa3b, v255
	v_exp_f32_e32 v240, v240
	v_exp_f32_e32 v241, v241
	v_add_f32_e32 v240, 1.0, v240
	v_add_f32_e32 v241, 1.0, v241
	v_rcp_f32_e32 v240, v240
	v_rcp_f32_e32 v241, v241
	v_mul_f32_e32 v254, v254, v240
	v_mul_f32_e32 v255, v255, v241
	v_mul_f32_e32 v254, v254, v62
	v_mul_f32_e32 v255, v255, v63
	v_cvt_pk_bf16_f32 v244, v254, v255
	v_lshlrev_b32_e32 v240, 16, v185
	v_and_b32_e32 v241, 0xffff0000, v185
	v_lshlrev_b32_e32 v242, 16, v189
	v_and_b32_e32 v243, 0xffff0000, v189
	v_lshlrev_b32_e32 v252, 16, v193
	v_and_b32_e32 v253, 0xffff0000, v193
	v_fma_f32 v254, v132, v240, v156
	v_fma_f32 v255, v133, v241, v157
	v_fma_f32 v254, v140, v242, v254
	v_fma_f32 v255, v141, v243, v255
	v_fma_f32 v254, v148, v252, v254
	v_fma_f32 v255, v149, v253, v255
	v_mul_f32_e32 v240, 0xbfb8aa3b, v254
	v_mul_f32_e32 v241, 0xbfb8aa3b, v255
	v_exp_f32_e32 v240, v240
	v_exp_f32_e32 v241, v241
	v_add_f32_e32 v240, 1.0, v240
	v_add_f32_e32 v241, 1.0, v241
	v_rcp_f32_e32 v240, v240
	v_rcp_f32_e32 v241, v241
	v_mul_f32_e32 v254, v254, v240
	v_mul_f32_e32 v255, v255, v241
	v_mul_f32_e32 v254, v254, v64
	v_mul_f32_e32 v255, v255, v65
	v_cvt_pk_bf16_f32 v245, v254, v255
	v_lshlrev_b32_e32 v240, 16, v186
	v_and_b32_e32 v241, 0xffff0000, v186
	v_lshlrev_b32_e32 v242, 16, v190
	v_and_b32_e32 v243, 0xffff0000, v190
	v_lshlrev_b32_e32 v252, 16, v194
	v_and_b32_e32 v253, 0xffff0000, v194
	v_fma_f32 v254, v134, v240, v158
	v_fma_f32 v255, v135, v241, v159
	v_fma_f32 v254, v142, v242, v254
	v_fma_f32 v255, v143, v243, v255
	v_fma_f32 v254, v150, v252, v254
	v_fma_f32 v255, v151, v253, v255
	v_mul_f32_e32 v240, 0xbfb8aa3b, v254
	v_mul_f32_e32 v241, 0xbfb8aa3b, v255
	v_exp_f32_e32 v240, v240
	v_exp_f32_e32 v241, v241
	v_add_f32_e32 v240, 1.0, v240
	v_add_f32_e32 v241, 1.0, v241
	v_rcp_f32_e32 v240, v240
	v_rcp_f32_e32 v241, v241
	v_mul_f32_e32 v254, v254, v240
	v_mul_f32_e32 v255, v255, v241
	v_mul_f32_e32 v254, v254, v58
	v_mul_f32_e32 v255, v255, v59
	v_cvt_pk_bf16_f32 v246, v254, v255
	v_lshlrev_b32_e32 v240, 16, v187
	v_and_b32_e32 v241, 0xffff0000, v187
	v_lshlrev_b32_e32 v242, 16, v191
	v_and_b32_e32 v243, 0xffff0000, v191
	v_lshlrev_b32_e32 v252, 16, v195
	v_and_b32_e32 v253, 0xffff0000, v195
	v_fma_f32 v254, v136, v240, v160
	v_fma_f32 v255, v137, v241, v161
	v_fma_f32 v254, v144, v242, v254
	v_fma_f32 v255, v145, v243, v255
	v_fma_f32 v254, v152, v252, v254
	v_fma_f32 v255, v153, v253, v255
	v_mul_f32_e32 v240, 0xbfb8aa3b, v254
	v_mul_f32_e32 v241, 0xbfb8aa3b, v255
	v_exp_f32_e32 v240, v240
	v_exp_f32_e32 v241, v241
	v_add_f32_e32 v240, 1.0, v240
	v_add_f32_e32 v241, 1.0, v241
	v_rcp_f32_e32 v240, v240
	v_rcp_f32_e32 v241, v241
	v_mul_f32_e32 v254, v254, v240
	v_mul_f32_e32 v255, v255, v241
	v_mul_f32_e32 v254, v254, v60
	v_mul_f32_e32 v255, v255, v61
	v_cvt_pk_bf16_f32 v247, v254, v255
	global_store_dwordx4 v[196:197], v[244:247], off
	v_add_u32_e32 v183, 0x9f, v176
	v_mad_i64_i32 v[222:223], s[0:1], v183, s14, v[180:181]
	v_lshl_add_u64 v[224:225], v[222:223], 0, s[98:99]
	v_lshl_add_u64 v[226:227], v[224:225], 0, s[98:99]
	v_lshl_add_u64 v[196:197], v[224:225], 0, s[100:101]
	global_load_dwordx4 v[184:187], v[222:223], off
	global_load_dwordx4 v[188:191], v[224:225], off
	global_load_dwordx4 v[192:195], v[226:227], off
	s_waitcnt vmcnt(4)
	v_lshlrev_b32_e32 v240, 16, v198
	v_and_b32_e32 v241, 0xffff0000, v198
	v_lshlrev_b32_e32 v242, 16, v202
	v_and_b32_e32 v243, 0xffff0000, v202
	v_lshlrev_b32_e32 v252, 16, v206
	v_and_b32_e32 v253, 0xffff0000, v206
	v_fma_f32 v254, v130, v240, v154
	v_fma_f32 v255, v131, v241, v155
	v_fma_f32 v254, v138, v242, v254
	v_fma_f32 v255, v139, v243, v255
	v_fma_f32 v254, v146, v252, v254
	v_fma_f32 v255, v147, v253, v255
	v_mul_f32_e32 v240, 0xbfb8aa3b, v254
	v_mul_f32_e32 v241, 0xbfb8aa3b, v255
	v_exp_f32_e32 v240, v240
	v_exp_f32_e32 v241, v241
	v_add_f32_e32 v240, 1.0, v240
	v_add_f32_e32 v241, 1.0, v241
	v_rcp_f32_e32 v240, v240
	v_rcp_f32_e32 v241, v241
	v_mul_f32_e32 v254, v254, v240
	v_mul_f32_e32 v255, v255, v241
	v_mul_f32_e32 v254, v254, v54
	v_mul_f32_e32 v255, v255, v55
	v_cvt_pk_bf16_f32 v248, v254, v255
	v_lshlrev_b32_e32 v240, 16, v199
	v_and_b32_e32 v241, 0xffff0000, v199
	v_lshlrev_b32_e32 v242, 16, v203
	v_and_b32_e32 v243, 0xffff0000, v203
	v_lshlrev_b32_e32 v252, 16, v207
	v_and_b32_e32 v253, 0xffff0000, v207
	v_fma_f32 v254, v132, v240, v156
	v_fma_f32 v255, v133, v241, v157
	v_fma_f32 v254, v140, v242, v254
	v_fma_f32 v255, v141, v243, v255
	v_fma_f32 v254, v148, v252, v254
	v_fma_f32 v255, v149, v253, v255
	v_mul_f32_e32 v240, 0xbfb8aa3b, v254
	v_mul_f32_e32 v241, 0xbfb8aa3b, v255
	v_exp_f32_e32 v240, v240
	v_exp_f32_e32 v241, v241
	v_add_f32_e32 v240, 1.0, v240
	v_add_f32_e32 v241, 1.0, v241
	v_rcp_f32_e32 v240, v240
	v_rcp_f32_e32 v241, v241
	v_mul_f32_e32 v254, v254, v240
	v_mul_f32_e32 v255, v255, v241
	v_mul_f32_e32 v254, v254, v56
	v_mul_f32_e32 v255, v255, v57
	v_cvt_pk_bf16_f32 v249, v254, v255
	v_lshlrev_b32_e32 v240, 16, v200
	v_and_b32_e32 v241, 0xffff0000, v200
	v_lshlrev_b32_e32 v242, 16, v204
	v_and_b32_e32 v243, 0xffff0000, v204
	v_lshlrev_b32_e32 v252, 16, v208
	v_and_b32_e32 v253, 0xffff0000, v208
; DI unsigned pack2(float a, float b) { f32x2_t v = {a, b}; bf16x2_t r = __builtin_convertvector(v, bf16x2_t); return __builtin_bit_cast(unsigned, r); }
; DI float lo2f(unsigned u) { return __uint_as_float(u << 16); }
; DI float hi2f(unsigned u) { return __uint_as_float(u & 0xffff0000u); }
; DI float sigmoidf_(float x) { return __builtin_amdgcn_rcpf(1.f + __builtin_amdgcn_exp2f(-1.4426950408889634f * x)); }
;   DI void operator()(const f32x4 (&acc)[2][2][4][2], const pg8::Unit& u, int wr, int wc, int fr, int fq) const {
;     ...
;           for (int bj = 0; bj < 2; ++bj) {
;             const f32x4 v0 = acc[ai][bj][m][0], v1 = acc[ai][bj][m][1];
;             const uint4 g = gs[m][bj];
;             f32x4 q0 = {lo2f(g.x) * v0[0], hi2f(g.x) * v0[1], lo2f(g.y) * v0[2], hi2f(g.y) * v0[3]};
;             f32x4 q1 = {lo2f(g.z) * v1[0], hi2f(g.z) * v1[1], lo2f(g.w) * v1[2], hi2f(g.w) * v1[3]};
;             st8(o0 + (size_t)(row0 + ai * 128 + m * 16) * DFF + col0 + bj * 128, q0, q1);
; DI void conv_phase(const Params& p, int l) {
;     ...
;     for (int i = 0; i < RUN; ++i) {
;       unpack8(rows[i + 2], nxt);
;       float o[8];
; #pragma unroll
;       for (int j = 0; j < 8; ++j) { const float g = w0[j] * prev[j] + w1[j] * cur[j] + w2[j] * nxt[j] + bb[j]; o[j] = g * sigmoidf_(g); }
;       uint4 oo; oo.x = pack2(o[0], o[1]); oo.y = pack2(o[2], o[3]); oo.z = pack2(o[4], o[5]); oo.w = pack2(o[6], o[7]);
;       *(uint4*)(GS + (size_t)(t0 + i) * DFF + c0) = oo;
	v_fma_f32 v254, v134, v240, v158
	v_fma_f32 v255, v135, v241, v159
	v_fma_f32 v254, v142, v242, v254
	v_fma_f32 v255, v143, v243, v255
	v_fma_f32 v254, v150, v252, v254
	v_fma_f32 v255, v151, v253, v255
	v_mul_f32_e32 v240, 0xbfb8aa3b, v254
	v_mul_f32_e32 v241, 0xbfb8aa3b, v255
	v_exp_f32_e32 v240, v240
	v_exp_f32_e32 v241, v241
	v_add_f32_e32 v240, 1.0, v240
	v_add_f32_e32 v241, 1.0, v241
	v_rcp_f32_e32 v240, v240
	v_rcp_f32_e32 v241, v241
	v_mul_f32_e32 v254, v254, v240
	v_mul_f32_e32 v255, v255, v241
	v_mul_f32_e32 v254, v254, v50
	v_mul_f32_e32 v255, v255, v51
	v_cvt_pk_bf16_f32 v250, v254, v255
	v_lshlrev_b32_e32 v240, 16, v201
	v_and_b32_e32 v241, 0xffff0000, v201
	v_lshlrev_b32_e32 v242, 16, v205
	v_and_b32_e32 v243, 0xffff0000, v205
	v_lshlrev_b32_e32 v252, 16, v209
	v_and_b32_e32 v253, 0xffff0000, v209
	v_fma_f32 v254, v136, v240, v160
	v_fma_f32 v255, v137, v241, v161
	v_fma_f32 v254, v144, v242, v254
	v_fma_f32 v255, v145, v243, v255
	v_fma_f32 v254, v152, v252, v254
	v_fma_f32 v255, v153, v253, v255
	v_mul_f32_e32 v240, 0xbfb8aa3b, v254
	v_mul_f32_e32 v241, 0xbfb8aa3b, v255
	v_exp_f32_e32 v240, v240
	v_exp_f32_e32 v241, v241
	v_add_f32_e32 v240, 1.0, v240
	v_add_f32_e32 v241, 1.0, v241
	v_rcp_f32_e32 v240, v240
	v_rcp_f32_e32 v241, v241
	v_mul_f32_e32 v254, v254, v240
	v_mul_f32_e32 v255, v255, v241
	v_mul_f32_e32 v254, v254, v52
	v_mul_f32_e32 v255, v255, v53
	v_cvt_pk_bf16_f32 v251, v254, v255
	global_store_dwordx4 v[220:221], v[248:251], off
	v_add_u32_e32 v183, 0xaf, v176
	v_mad_i64_i32 v[222:223], s[0:1], v183, s14, v[180:181]
	v_lshl_add_u64 v[224:225], v[222:223], 0, s[98:99]
	v_lshl_add_u64 v[226:227], v[224:225], 0, s[98:99]
	v_lshl_add_u64 v[220:221], v[224:225], 0, s[100:101]
	global_load_dwordx4 v[198:201], v[222:223], off
	global_load_dwordx4 v[202:205], v[224:225], off
	global_load_dwordx4 v[206:209], v[226:227], off
	s_waitcnt vmcnt(4)
	v_lshlrev_b32_e32 v240, 16, v184
	v_and_b32_e32 v241, 0xffff0000, v184
	v_lshlrev_b32_e32 v242, 16, v188
	v_and_b32_e32 v243, 0xffff0000, v188
	v_lshlrev_b32_e32 v252, 16, v192
	v_and_b32_e32 v253, 0xffff0000, v192
	v_fma_f32 v254, v130, v240, v154
	v_fma_f32 v255, v131, v241, v155
	v_fma_f32 v254, v138, v242, v254
	v_fma_f32 v255, v139, v243, v255
	v_fma_f32 v254, v146, v252, v254
	v_fma_f32 v255, v147, v253, v255
	v_mul_f32_e32 v240, 0xbfb8aa3b, v254
	v_mul_f32_e32 v241, 0xbfb8aa3b, v255
	v_exp_f32_e32 v240, v240
	v_exp_f32_e32 v241, v241
	v_add_f32_e32 v240, 1.0, v240
	v_add_f32_e32 v241, 1.0, v241
	v_rcp_f32_e32 v240, v240
	v_rcp_f32_e32 v241, v241
	v_mul_f32_e32 v254, v254, v240
	v_mul_f32_e32 v255, v255, v241
	v_mul_f32_e32 v254, v254, v38
	v_mul_f32_e32 v255, v255, v39
	v_cvt_pk_bf16_f32 v244, v254, v255
	v_lshlrev_b32_e32 v240, 16, v185
	v_and_b32_e32 v241, 0xffff0000, v185
	v_lshlrev_b32_e32 v242, 16, v189
	v_and_b32_e32 v243, 0xffff0000, v189
	v_lshlrev_b32_e32 v252, 16, v193
	v_and_b32_e32 v253, 0xffff0000, v193
	v_fma_f32 v254, v132, v240, v156
	v_fma_f32 v255, v133, v241, v157
	v_fma_f32 v254, v140, v242, v254
	v_fma_f32 v255, v141, v243, v255
	v_fma_f32 v254, v148, v252, v254
	v_fma_f32 v255, v149, v253, v255
	v_mul_f32_e32 v240, 0xbfb8aa3b, v254
	v_mul_f32_e32 v241, 0xbfb8aa3b, v255
	v_exp_f32_e32 v240, v240
	v_exp_f32_e32 v241, v241
	v_add_f32_e32 v240, 1.0, v240
	v_add_f32_e32 v241, 1.0, v241
	v_rcp_f32_e32 v240, v240
	v_rcp_f32_e32 v241, v241
	v_mul_f32_e32 v254, v254, v240
	v_mul_f32_e32 v255, v255, v241
	v_mul_f32_e32 v254, v254, v40
	v_mul_f32_e32 v255, v255, v41
	v_cvt_pk_bf16_f32 v245, v254, v255
	v_lshlrev_b32_e32 v240, 16, v186
	v_and_b32_e32 v241, 0xffff0000, v186
	v_lshlrev_b32_e32 v242, 16, v190
	v_and_b32_e32 v243, 0xffff0000, v190
	v_lshlrev_b32_e32 v252, 16, v194
	v_and_b32_e32 v253, 0xffff0000, v194
	v_fma_f32 v254, v134, v240, v158
	v_fma_f32 v255, v135, v241, v159
	v_fma_f32 v254, v142, v242, v254
	v_fma_f32 v255, v143, v243, v255
	v_fma_f32 v254, v150, v252, v254
	v_fma_f32 v255, v151, v253, v255
	v_mul_f32_e32 v240, 0xbfb8aa3b, v254
	v_mul_f32_e32 v241, 0xbfb8aa3b, v255
	v_exp_f32_e32 v240, v240
	v_exp_f32_e32 v241, v241
	v_add_f32_e32 v240, 1.0, v240
	v_add_f32_e32 v241, 1.0, v241
	v_rcp_f32_e32 v240, v240
	v_rcp_f32_e32 v241, v241
	v_mul_f32_e32 v254, v254, v240
	v_mul_f32_e32 v255, v255, v241
	v_mul_f32_e32 v254, v254, v34
	v_mul_f32_e32 v255, v255, v35
	v_cvt_pk_bf16_f32 v246, v254, v255
	v_lshlrev_b32_e32 v240, 16, v187
	v_and_b32_e32 v241, 0xffff0000, v187
	v_lshlrev_b32_e32 v242, 16, v191
	v_and_b32_e32 v243, 0xffff0000, v191
	v_lshlrev_b32_e32 v252, 16, v195
	v_and_b32_e32 v253, 0xffff0000, v195
	v_fma_f32 v254, v136, v240, v160
	v_fma_f32 v255, v137, v241, v161
	v_fma_f32 v254, v144, v242, v254
	v_fma_f32 v255, v145, v243, v255
	v_fma_f32 v254, v152, v252, v254
	v_fma_f32 v255, v153, v253, v255
	v_mul_f32_e32 v240, 0xbfb8aa3b, v254
	v_mul_f32_e32 v241, 0xbfb8aa3b, v255
	v_exp_f32_e32 v240, v240
	v_exp_f32_e32 v241, v241
	v_add_f32_e32 v240, 1.0, v240
	v_add_f32_e32 v241, 1.0, v241
	v_rcp_f32_e32 v240, v240
	v_rcp_f32_e32 v241, v241
	v_mul_f32_e32 v254, v254, v240
	v_mul_f32_e32 v255, v255, v241
	v_mul_f32_e32 v254, v254, v36
	v_mul_f32_e32 v255, v255, v37
	v_cvt_pk_bf16_f32 v247, v254, v255
	global_store_dwordx4 v[196:197], v[244:247], off
	s_waitcnt vmcnt(1)
; DI unsigned pack2(float a, float b) { f32x2_t v = {a, b}; bf16x2_t r = __builtin_convertvector(v, bf16x2_t); return __builtin_bit_cast(unsigned, r); }
; DI float lo2f(unsigned u) { return __uint_as_float(u << 16); }
; DI float hi2f(unsigned u) { return __uint_as_float(u & 0xffff0000u); }
; DI float sigmoidf_(float x) { return __builtin_amdgcn_rcpf(1.f + __builtin_amdgcn_exp2f(-1.4426950408889634f * x)); }
;   DI void operator()(const f32x4 (&acc)[2][2][4][2], const pg8::Unit& u, int wr, int wc, int fr, int fq) const {
;     ...
;           for (int bj = 0; bj < 2; ++bj) {
;             const f32x4 v0 = acc[ai][bj][m][0], v1 = acc[ai][bj][m][1];
;             const uint4 g = gs[m][bj];
;             f32x4 q0 = {lo2f(g.x) * v0[0], hi2f(g.x) * v0[1], lo2f(g.y) * v0[2], hi2f(g.y) * v0[3]};
;             f32x4 q1 = {lo2f(g.z) * v1[0], hi2f(g.z) * v1[1], lo2f(g.w) * v1[2], hi2f(g.w) * v1[3]};
;             st8(o0 + (size_t)(row0 + ai * 128 + m * 16) * DFF + col0 + bj * 128, q0, q1);
; DI void conv_phase(const Params& p, int l) {
;     ...
;     rows[0] = (s0 > 0) ? *(const uint4*)(gp - DFF) : z;
; #pragma unroll
;     for (int i = 0; i < RUN; ++i) rows[i + 1] = *(const uint4*)(gp + (size_t)i * DFF);
;     rows[RUN + 1] = (s0 + RUN - 1 < S - 1) ? *(const uint4*)(gp + (size_t)RUN * DFF) : z;
;     float w0[8], w1[8], w2[8], bb[8];
;     load8f(cw + c0, w0); load8f(cw + DFF + c0, w1); load8f(cw + 2 * DFF + c0, w2); load8f(cb + c0, bb);
;     float prev[8], cur[8], nxt[8];
;     unpack8(rows[0], prev); unpack8(rows[1], cur);
; #pragma unroll
;     for (int i = 0; i < RUN; ++i) {
;       unpack8(rows[i + 2], nxt);
;       float o[8];
; #pragma unroll
;       for (int j = 0; j < 8; ++j) { const float g = w0[j] * prev[j] + w1[j] * cur[j] + w2[j] * nxt[j] + bb[j]; o[j] = g * sigmoidf_(g); }
;       uint4 oo; oo.x = pack2(o[0], o[1]); oo.y = pack2(o[2], o[3]); oo.z = pack2(o[4], o[5]); oo.w = pack2(o[6], o[7]);
;       *(uint4*)(GS + (size_t)(t0 + i) * DFF + c0) = oo;
	v_add_u32_e32 v183, 0xb0, v176
	v_and_b32_e32 v183, 0x1fff, v183
	v_cmp_eq_u32_e32 vcc, 0x1fff, v183
	v_cndmask_b32_e64 v206, v206, 0, vcc
	v_cndmask_b32_e64 v207, v207, 0, vcc
	v_cndmask_b32_e64 v208, v208, 0, vcc
	v_cndmask_b32_e64 v209, v209, 0, vcc
	v_lshlrev_b32_e32 v240, 16, v198
	v_and_b32_e32 v241, 0xffff0000, v198
	v_lshlrev_b32_e32 v242, 16, v202
	v_and_b32_e32 v243, 0xffff0000, v202
	v_lshlrev_b32_e32 v252, 16, v206
	v_and_b32_e32 v253, 0xffff0000, v206
	v_fma_f32 v254, v130, v240, v154
	v_fma_f32 v255, v131, v241, v155
	v_fma_f32 v254, v138, v242, v254
	v_fma_f32 v255, v139, v243, v255
	v_fma_f32 v254, v146, v252, v254
	v_fma_f32 v255, v147, v253, v255
	v_mul_f32_e32 v240, 0xbfb8aa3b, v254
	v_mul_f32_e32 v241, 0xbfb8aa3b, v255
	v_exp_f32_e32 v240, v240
	v_exp_f32_e32 v241, v241
	v_add_f32_e32 v240, 1.0, v240
	v_add_f32_e32 v241, 1.0, v241
	v_rcp_f32_e32 v240, v240
	v_rcp_f32_e32 v241, v241
	v_mul_f32_e32 v254, v254, v240
	v_mul_f32_e32 v255, v255, v241
	v_mul_f32_e32 v254, v254, v22
	v_mul_f32_e32 v255, v255, v23
	v_cvt_pk_bf16_f32 v248, v254, v255
	v_lshlrev_b32_e32 v240, 16, v199
	v_and_b32_e32 v241, 0xffff0000, v199
	v_lshlrev_b32_e32 v242, 16, v203
	v_and_b32_e32 v243, 0xffff0000, v203
	v_lshlrev_b32_e32 v252, 16, v207
	v_and_b32_e32 v253, 0xffff0000, v207
	v_fma_f32 v254, v132, v240, v156
	v_fma_f32 v255, v133, v241, v157
	v_fma_f32 v254, v140, v242, v254
	v_fma_f32 v255, v141, v243, v255
	v_fma_f32 v254, v148, v252, v254
	v_fma_f32 v255, v149, v253, v255
	v_mul_f32_e32 v240, 0xbfb8aa3b, v254
	v_mul_f32_e32 v241, 0xbfb8aa3b, v255
	v_exp_f32_e32 v240, v240
	v_exp_f32_e32 v241, v241
	v_add_f32_e32 v240, 1.0, v240
	v_add_f32_e32 v241, 1.0, v241
	v_rcp_f32_e32 v240, v240
	v_rcp_f32_e32 v241, v241
	v_mul_f32_e32 v254, v254, v240
	v_mul_f32_e32 v255, v255, v241
	v_mul_f32_e32 v254, v254, v24
	v_mul_f32_e32 v255, v255, v25
	v_cvt_pk_bf16_f32 v249, v254, v255
	v_lshlrev_b32_e32 v240, 16, v200
	v_and_b32_e32 v241, 0xffff0000, v200
	v_lshlrev_b32_e32 v242, 16, v204
	v_and_b32_e32 v243, 0xffff0000, v204
	v_lshlrev_b32_e32 v252, 16, v208
	v_and_b32_e32 v253, 0xffff0000, v208
	v_fma_f32 v254, v134, v240, v158
	v_fma_f32 v255, v135, v241, v159
	v_fma_f32 v254, v142, v242, v254
	v_fma_f32 v255, v143, v243, v255
	v_fma_f32 v254, v150, v252, v254
	v_fma_f32 v255, v151, v253, v255
	v_mul_f32_e32 v240, 0xbfb8aa3b, v254
	v_mul_f32_e32 v241, 0xbfb8aa3b, v255
	v_exp_f32_e32 v240, v240
	v_exp_f32_e32 v241, v241
	v_add_f32_e32 v240, 1.0, v240
	v_add_f32_e32 v241, 1.0, v241
	v_rcp_f32_e32 v240, v240
	v_rcp_f32_e32 v241, v241
	v_mul_f32_e32 v254, v254, v240
	v_mul_f32_e32 v255, v255, v241
	v_mul_f32_e32 v254, v254, v18
	v_mul_f32_e32 v255, v255, v19
	v_cvt_pk_bf16_f32 v250, v254, v255
	v_lshlrev_b32_e32 v240, 16, v201
	v_and_b32_e32 v241, 0xffff0000, v201
	v_lshlrev_b32_e32 v242, 16, v205
	v_and_b32_e32 v243, 0xffff0000, v205
	v_lshlrev_b32_e32 v252, 16, v209
	v_and_b32_e32 v253, 0xffff0000, v209
	v_fma_f32 v254, v136, v240, v160
	v_fma_f32 v255, v137, v241, v161
	v_fma_f32 v254, v144, v242, v254
	v_fma_f32 v255, v145, v243, v255
	v_fma_f32 v254, v152, v252, v254
	v_fma_f32 v255, v153, v253, v255
	v_mul_f32_e32 v240, 0xbfb8aa3b, v254
	v_mul_f32_e32 v241, 0xbfb8aa3b, v255
	v_exp_f32_e32 v240, v240
	v_exp_f32_e32 v241, v241
	v_add_f32_e32 v240, 1.0, v240
	v_add_f32_e32 v241, 1.0, v241
	v_rcp_f32_e32 v240, v240
	v_rcp_f32_e32 v241, v241
	v_mul_f32_e32 v254, v254, v240
	v_mul_f32_e32 v255, v255, v241
	v_mul_f32_e32 v254, v254, v20
	v_mul_f32_e32 v255, v255, v21
	v_cvt_pk_bf16_f32 v251, v254, v255
	global_store_dwordx4 v[220:221], v[248:251], off
	v_readlane_b32 s98, v237, 62
	v_readlane_b32 s100, v238, 0
	v_readlane_b32 s101, v238, 1
	s_mul_i32 s98, s98, 0xab
	s_bfe_u32 s98, s98, 0x6000a
	s_mul_i32 s99, s98, 0x8400
	s_add_u32 s100, s100, s99
	s_addc_u32 s101, s101, 0
	s_nop 3
	global_load_dwordx4 v[130:133], v182, s[100:101] offset:512
	global_load_dwordx4 v[134:137], v182, s[100:101] offset:528
	s_add_u32 s100, s100, 0x2c00
	s_addc_u32 s101, s101, 0
	global_load_dwordx4 v[138:141], v182, s[100:101] offset:512
	global_load_dwordx4 v[142:145], v182, s[100:101] offset:528
	s_add_u32 s100, s100, 0x2c00
	s_addc_u32 s101, s101, 0
	global_load_dwordx4 v[146:149], v182, s[100:101] offset:512
	global_load_dwordx4 v[150:153], v182, s[100:101] offset:528
	v_readlane_b32 s100, v238, 2
	v_readlane_b32 s101, v238, 3
	s_mul_i32 s99, s98, 0x2c00
	s_add_u32 s100, s100, s99
	s_addc_u32 s101, s101, 0
	s_nop 3
	global_load_dwordx4 v[154:157], v182, s[100:101] offset:512
	global_load_dwordx4 v[158:161], v182, s[100:101] offset:528
	s_mov_b32 s98, 0x1600
	s_mov_b32 s99, 0
	s_mov_b32 s100, 0x16000000
	s_mov_b32 s101, 0
	v_add_u32_e32 v183, -1, v176
	v_mad_i64_i32 v[222:223], s[0:1], v183, s14, v[180:181]
	v_lshl_add_u64 v[224:225], v[222:223], 0, s[98:99]
	v_lshl_add_u64 v[226:227], v[224:225], 0, s[98:99]
	v_lshl_add_u64 v[196:197], v[224:225], 0, s[100:101]
	global_load_dwordx4 v[184:187], v[222:223], off offset:256
	global_load_dwordx4 v[188:191], v[224:225], off offset:256
	global_load_dwordx4 v[192:195], v[226:227], off offset:256
	v_add_u32_e32 v183, 0xf, v176
	v_mad_i64_i32 v[222:223], s[0:1], v183, s14, v[180:181]
	v_lshl_add_u64 v[224:225], v[222:223], 0, s[98:99]
	v_lshl_add_u64 v[226:227], v[224:225], 0, s[98:99]
	v_lshl_add_u64 v[220:221], v[224:225], 0, s[100:101]
	global_load_dwordx4 v[198:201], v[222:223], off offset:256
	global_load_dwordx4 v[202:205], v[224:225], off offset:256
	global_load_dwordx4 v[206:209], v[226:227], off offset:256
	s_waitcnt vmcnt(3)
; DI unsigned pack2(float a, float b) { f32x2_t v = {a, b}; bf16x2_t r = __builtin_convertvector(v, bf16x2_t); return __builtin_bit_cast(unsigned, r); }
; DI float lo2f(unsigned u) { return __uint_as_float(u << 16); }
; DI float hi2f(unsigned u) { return __uint_as_float(u & 0xffff0000u); }
; DI float sigmoidf_(float x) { return __builtin_amdgcn_rcpf(1.f + __builtin_amdgcn_exp2f(-1.4426950408889634f * x)); }
;   DI void operator()(const f32x4 (&acc)[2][2][4][2], const pg8::Unit& u, int wr, int wc, int fr, int fq) const {
;     ...
;           for (int bj = 0; bj < 2; ++bj) {
;             const f32x4 v0 = acc[ai][bj][m][0], v1 = acc[ai][bj][m][1];
;             const uint4 g = gs[m][bj];
;             f32x4 q0 = {lo2f(g.x) * v0[0], hi2f(g.x) * v0[1], lo2f(g.y) * v0[2], hi2f(g.y) * v0[3]};
;             f32x4 q1 = {lo2f(g.z) * v1[0], hi2f(g.z) * v1[1], lo2f(g.w) * v1[2], hi2f(g.w) * v1[3]};
;             st8(o0 + (size_t)(row0 + ai * 128 + m * 16) * DFF + col0 + bj * 128, q0, q1);
; DI void conv_phase(const Params& p, int l) {
;     ...
;     rows[0] = (s0 > 0) ? *(const uint4*)(gp - DFF) : z;
; #pragma unroll
;     for (int i = 0; i < RUN; ++i) rows[i + 1] = *(const uint4*)(gp + (size_t)i * DFF);
;     rows[RUN + 1] = (s0 + RUN - 1 < S - 1) ? *(const uint4*)(gp + (size_t)RUN * DFF) : z;
;     float w0[8], w1[8], w2[8], bb[8];
;     load8f(cw + c0, w0); load8f(cw + DFF + c0, w1); load8f(cw + 2 * DFF + c0, w2); load8f(cb + c0, bb);
;     float prev[8], cur[8], nxt[8];
;     unpack8(rows[0], prev); unpack8(rows[1], cur);
; #pragma unroll
;     for (int i = 0; i < RUN; ++i) {
;       unpack8(rows[i + 2], nxt);
;       float o[8];
; #pragma unroll
;       for (int j = 0; j < 8; ++j) { const float g = w0[j] * prev[j] + w1[j] * cur[j] + w2[j] * nxt[j] + bb[j]; o[j] = g * sigmoidf_(g); }
;       uint4 oo; oo.x = pack2(o[0], o[1]); oo.y = pack2(o[2], o[3]); oo.z = pack2(o[4], o[5]); oo.w = pack2(o[6], o[7]);
;       *(uint4*)(GS + (size_t)(t0 + i) * DFF + c0) = oo;
	v_and_b32_e32 v183, 0x1fff, v176
	v_cmp_eq_u32_e32 vcc, 0, v183
	v_cndmask_b32_e64 v184, v184, 0, vcc
	v_cndmask_b32_e64 v185, v185, 0, vcc
	v_cndmask_b32_e64 v186, v186, 0, vcc
	v_cndmask_b32_e64 v187, v187, 0, vcc
	v_lshlrev_b32_e32 v240, 16, v184
	v_and_b32_e32 v241, 0xffff0000, v184
	v_lshlrev_b32_e32 v242, 16, v188
	v_and_b32_e32 v243, 0xffff0000, v188
	v_lshlrev_b32_e32 v252, 16, v192
	v_and_b32_e32 v253, 0xffff0000, v192
	v_fma_f32 v254, v130, v240, v154
	v_fma_f32 v255, v131, v241, v155
	v_fma_f32 v254, v138, v242, v254
	v_fma_f32 v255, v139, v243, v255
	v_fma_f32 v254, v146, v252, v254
	v_fma_f32 v255, v147, v253, v255
	v_mul_f32_e32 v240, 0xbfb8aa3b, v254
	v_mul_f32_e32 v241, 0xbfb8aa3b, v255
	v_exp_f32_e32 v240, v240
	v_exp_f32_e32 v241, v241
	v_add_f32_e32 v240, 1.0, v240
	v_add_f32_e32 v241, 1.0, v241
	v_rcp_f32_e32 v240, v240
	v_rcp_f32_e32 v241, v241
	v_mul_f32_e32 v254, v254, v240
	v_mul_f32_e32 v255, v255, v241
	v_mul_f32_e32 v254, v254, v110
	v_mul_f32_e32 v255, v255, v111
	v_cvt_pk_bf16_f32 v244, v254, v255
	v_lshlrev_b32_e32 v240, 16, v185
	v_and_b32_e32 v241, 0xffff0000, v185
	v_lshlrev_b32_e32 v242, 16, v189
	v_and_b32_e32 v243, 0xffff0000, v189
	v_lshlrev_b32_e32 v252, 16, v193
	v_and_b32_e32 v253, 0xffff0000, v193
	v_fma_f32 v254, v132, v240, v156
	v_fma_f32 v255, v133, v241, v157
	v_fma_f32 v254, v140, v242, v254
	v_fma_f32 v255, v141, v243, v255
	v_fma_f32 v254, v148, v252, v254
	v_fma_f32 v255, v149, v253, v255
	v_mul_f32_e32 v240, 0xbfb8aa3b, v254
	v_mul_f32_e32 v241, 0xbfb8aa3b, v255
	v_exp_f32_e32 v240, v240
	v_exp_f32_e32 v241, v241
	v_add_f32_e32 v240, 1.0, v240
	v_add_f32_e32 v241, 1.0, v241
	v_rcp_f32_e32 v240, v240
	v_rcp_f32_e32 v241, v241
	v_mul_f32_e32 v254, v254, v240
	v_mul_f32_e32 v255, v255, v241
	v_mul_f32_e32 v254, v254, v112
	v_mul_f32_e32 v255, v255, v113
	v_cvt_pk_bf16_f32 v245, v254, v255
	v_lshlrev_b32_e32 v240, 16, v186
	v_and_b32_e32 v241, 0xffff0000, v186
	v_lshlrev_b32_e32 v242, 16, v190
	v_and_b32_e32 v243, 0xffff0000, v190
	v_lshlrev_b32_e32 v252, 16, v194
	v_and_b32_e32 v253, 0xffff0000, v194
	v_fma_f32 v254, v134, v240, v158
	v_fma_f32 v255, v135, v241, v159
	v_fma_f32 v254, v142, v242, v254
	v_fma_f32 v255, v143, v243, v255
	v_fma_f32 v254, v150, v252, v254
	v_fma_f32 v255, v151, v253, v255
	v_mul_f32_e32 v240, 0xbfb8aa3b, v254
	v_mul_f32_e32 v241, 0xbfb8aa3b, v255
	v_exp_f32_e32 v240, v240
	v_exp_f32_e32 v241, v241
	v_add_f32_e32 v240, 1.0, v240
	v_add_f32_e32 v241, 1.0, v241
	v_rcp_f32_e32 v240, v240
	v_rcp_f32_e32 v241, v241
	v_mul_f32_e32 v254, v254, v240
	v_mul_f32_e32 v255, v255, v241
	v_mul_f32_e32 v254, v254, v106
	v_mul_f32_e32 v255, v255, v107
	v_cvt_pk_bf16_f32 v246, v254, v255
	v_lshlrev_b32_e32 v240, 16, v187
	v_and_b32_e32 v241, 0xffff0000, v187
	v_lshlrev_b32_e32 v242, 16, v191
	v_and_b32_e32 v243, 0xffff0000, v191
	v_lshlrev_b32_e32 v252, 16, v195
	v_and_b32_e32 v253, 0xffff0000, v195
	v_fma_f32 v254, v136, v240, v160
	v_fma_f32 v255, v137, v241, v161
	v_fma_f32 v254, v144, v242, v254
	v_fma_f32 v255, v145, v243, v255
	v_fma_f32 v254, v152, v252, v254
	v_fma_f32 v255, v153, v253, v255
	v_mul_f32_e32 v240, 0xbfb8aa3b, v254
	v_mul_f32_e32 v241, 0xbfb8aa3b, v255
	v_exp_f32_e32 v240, v240
	v_exp_f32_e32 v241, v241
	v_add_f32_e32 v240, 1.0, v240
	v_add_f32_e32 v241, 1.0, v241
	v_rcp_f32_e32 v240, v240
	v_rcp_f32_e32 v241, v241
	v_mul_f32_e32 v254, v254, v240
	v_mul_f32_e32 v255, v255, v241
	v_mul_f32_e32 v254, v254, v108
	v_mul_f32_e32 v255, v255, v109
	v_cvt_pk_bf16_f32 v247, v254, v255
	global_store_dwordx4 v[196:197], v[244:247], off offset:256
	v_add_u32_e32 v183, 0x1f, v176
	v_mad_i64_i32 v[222:223], s[0:1], v183, s14, v[180:181]
	v_lshl_add_u64 v[224:225], v[222:223], 0, s[98:99]
	v_lshl_add_u64 v[226:227], v[224:225], 0, s[98:99]
	v_lshl_add_u64 v[196:197], v[224:225], 0, s[100:101]
	global_load_dwordx4 v[184:187], v[222:223], off offset:256
	global_load_dwordx4 v[188:191], v[224:225], off offset:256
	global_load_dwordx4 v[192:195], v[226:227], off offset:256
	s_waitcnt vmcnt(4)
	v_lshlrev_b32_e32 v240, 16, v198
	v_and_b32_e32 v241, 0xffff0000, v198
	v_lshlrev_b32_e32 v242, 16, v202
	v_and_b32_e32 v243, 0xffff0000, v202
	v_lshlrev_b32_e32 v252, 16, v206
	v_and_b32_e32 v253, 0xffff0000, v206
	v_fma_f32 v254, v130, v240, v154
	v_fma_f32 v255, v131, v241, v155
	v_fma_f32 v254, v138, v242, v254
	v_fma_f32 v255, v139, v243, v255
	v_fma_f32 v254, v146, v252, v254
	v_fma_f32 v255, v147, v253, v255
	v_mul_f32_e32 v240, 0xbfb8aa3b, v254
	v_mul_f32_e32 v241, 0xbfb8aa3b, v255
	v_exp_f32_e32 v240, v240
	v_exp_f32_e32 v241, v241
	v_add_f32_e32 v240, 1.0, v240
	v_add_f32_e32 v241, 1.0, v241
	v_rcp_f32_e32 v240, v240
	v_rcp_f32_e32 v241, v241
	v_mul_f32_e32 v254, v254, v240
	v_mul_f32_e32 v255, v255, v241
	v_mul_f32_e32 v254, v254, v94
	v_mul_f32_e32 v255, v255, v95
	v_cvt_pk_bf16_f32 v248, v254, v255
	v_lshlrev_b32_e32 v240, 16, v199
	v_and_b32_e32 v241, 0xffff0000, v199
	v_lshlrev_b32_e32 v242, 16, v203
	v_and_b32_e32 v243, 0xffff0000, v203
	v_lshlrev_b32_e32 v252, 16, v207
	v_and_b32_e32 v253, 0xffff0000, v207
	v_fma_f32 v254, v132, v240, v156
	v_fma_f32 v255, v133, v241, v157
	v_fma_f32 v254, v140, v242, v254
	v_fma_f32 v255, v141, v243, v255
	v_fma_f32 v254, v148, v252, v254
	v_fma_f32 v255, v149, v253, v255
	v_mul_f32_e32 v240, 0xbfb8aa3b, v254
	v_mul_f32_e32 v241, 0xbfb8aa3b, v255
	v_exp_f32_e32 v240, v240
	v_exp_f32_e32 v241, v241
	v_add_f32_e32 v240, 1.0, v240
	v_add_f32_e32 v241, 1.0, v241
	v_rcp_f32_e32 v240, v240
	v_rcp_f32_e32 v241, v241
	v_mul_f32_e32 v254, v254, v240
	v_mul_f32_e32 v255, v255, v241
	v_mul_f32_e32 v254, v254, v96
	v_mul_f32_e32 v255, v255, v97
; DI unsigned pack2(float a, float b) { f32x2_t v = {a, b}; bf16x2_t r = __builtin_convertvector(v, bf16x2_t); return __builtin_bit_cast(unsigned, r); }
; DI float lo2f(unsigned u) { return __uint_as_float(u << 16); }
; DI float hi2f(unsigned u) { return __uint_as_float(u & 0xffff0000u); }
; DI float sigmoidf_(float x) { return __builtin_amdgcn_rcpf(1.f + __builtin_amdgcn_exp2f(-1.4426950408889634f * x)); }
;   DI void operator()(const f32x4 (&acc)[2][2][4][2], const pg8::Unit& u, int wr, int wc, int fr, int fq) const {
;     ...
;           for (int bj = 0; bj < 2; ++bj) {
;             const f32x4 v0 = acc[ai][bj][m][0], v1 = acc[ai][bj][m][1];
;             const uint4 g = gs[m][bj];
;             f32x4 q0 = {lo2f(g.x) * v0[0], hi2f(g.x) * v0[1], lo2f(g.y) * v0[2], hi2f(g.y) * v0[3]};
;             f32x4 q1 = {lo2f(g.z) * v1[0], hi2f(g.z) * v1[1], lo2f(g.w) * v1[2], hi2f(g.w) * v1[3]};
;             st8(o0 + (size_t)(row0 + ai * 128 + m * 16) * DFF + col0 + bj * 128, q0, q1);
; DI void conv_phase(const Params& p, int l) {
;     ...
;     for (int i = 0; i < RUN; ++i) {
;       unpack8(rows[i + 2], nxt);
;       float o[8];
; #pragma unroll
;       for (int j = 0; j < 8; ++j) { const float g = w0[j] * prev[j] + w1[j] * cur[j] + w2[j] * nxt[j] + bb[j]; o[j] = g * sigmoidf_(g); }
;       uint4 oo; oo.x = pack2(o[0], o[1]); oo.y = pack2(o[2], o[3]); oo.z = pack2(o[4], o[5]); oo.w = pack2(o[6], o[7]);
;       *(uint4*)(GS + (size_t)(t0 + i) * DFF + c0) = oo;
	v_cvt_pk_bf16_f32 v249, v254, v255
	v_lshlrev_b32_e32 v240, 16, v200
	v_and_b32_e32 v241, 0xffff0000, v200
	v_lshlrev_b32_e32 v242, 16, v204
	v_and_b32_e32 v243, 0xffff0000, v204
	v_lshlrev_b32_e32 v252, 16, v208
	v_and_b32_e32 v253, 0xffff0000, v208
	v_fma_f32 v254, v134, v240, v158
	v_fma_f32 v255, v135, v241, v159
	v_fma_f32 v254, v142, v242, v254
	v_fma_f32 v255, v143, v243, v255
	v_fma_f32 v254, v150, v252, v254
	v_fma_f32 v255, v151, v253, v255
	v_mul_f32_e32 v240, 0xbfb8aa3b, v254
	v_mul_f32_e32 v241, 0xbfb8aa3b, v255
	v_exp_f32_e32 v240, v240
	v_exp_f32_e32 v241, v241
	v_add_f32_e32 v240, 1.0, v240
	v_add_f32_e32 v241, 1.0, v241
	v_rcp_f32_e32 v240, v240
	v_rcp_f32_e32 v241, v241
	v_mul_f32_e32 v254, v254, v240
	v_mul_f32_e32 v255, v255, v241
	v_mul_f32_e32 v254, v254, v90
	v_mul_f32_e32 v255, v255, v91
	v_cvt_pk_bf16_f32 v250, v254, v255
	v_lshlrev_b32_e32 v240, 16, v201
	v_and_b32_e32 v241, 0xffff0000, v201
	v_lshlrev_b32_e32 v242, 16, v205
	v_and_b32_e32 v243, 0xffff0000, v205
	v_lshlrev_b32_e32 v252, 16, v209
	v_and_b32_e32 v253, 0xffff0000, v209
	v_fma_f32 v254, v136, v240, v160
	v_fma_f32 v255, v137, v241, v161
	v_fma_f32 v254, v144, v242, v254
	v_fma_f32 v255, v145, v243, v255
	v_fma_f32 v254, v152, v252, v254
	v_fma_f32 v255, v153, v253, v255
	v_mul_f32_e32 v240, 0xbfb8aa3b, v254
	v_mul_f32_e32 v241, 0xbfb8aa3b, v255
	v_exp_f32_e32 v240, v240
	v_exp_f32_e32 v241, v241
	v_add_f32_e32 v240, 1.0, v240
	v_add_f32_e32 v241, 1.0, v241
	v_rcp_f32_e32 v240, v240
	v_rcp_f32_e32 v241, v241
	v_mul_f32_e32 v254, v254, v240
	v_mul_f32_e32 v255, v255, v241
	v_mul_f32_e32 v254, v254, v92
	v_mul_f32_e32 v255, v255, v93
	v_cvt_pk_bf16_f32 v251, v254, v255
	global_store_dwordx4 v[220:221], v[248:251], off offset:256
	v_add_u32_e32 v183, 0x2f, v176
	v_mad_i64_i32 v[222:223], s[0:1], v183, s14, v[180:181]
	v_lshl_add_u64 v[224:225], v[222:223], 0, s[98:99]
	v_lshl_add_u64 v[226:227], v[224:225], 0, s[98:99]
	v_lshl_add_u64 v[220:221], v[224:225], 0, s[100:101]
	global_load_dwordx4 v[198:201], v[222:223], off offset:256
	global_load_dwordx4 v[202:205], v[224:225], off offset:256
	global_load_dwordx4 v[206:209], v[226:227], off offset:256
	s_waitcnt vmcnt(4)
	v_lshlrev_b32_e32 v240, 16, v184
	v_and_b32_e32 v241, 0xffff0000, v184
	v_lshlrev_b32_e32 v242, 16, v188
	v_and_b32_e32 v243, 0xffff0000, v188
	v_lshlrev_b32_e32 v252, 16, v192
	v_and_b32_e32 v253, 0xffff0000, v192
	v_fma_f32 v254, v130, v240, v154
	v_fma_f32 v255, v131, v241, v155
	v_fma_f32 v254, v138, v242, v254
	v_fma_f32 v255, v139, v243, v255
	v_fma_f32 v254, v146, v252, v254
	v_fma_f32 v255, v147, v253, v255
	v_mul_f32_e32 v240, 0xbfb8aa3b, v254
	v_mul_f32_e32 v241, 0xbfb8aa3b, v255
	v_exp_f32_e32 v240, v240
	v_exp_f32_e32 v241, v241
	v_add_f32_e32 v240, 1.0, v240
	v_add_f32_e32 v241, 1.0, v241
	v_rcp_f32_e32 v240, v240
	v_rcp_f32_e32 v241, v241
	v_mul_f32_e32 v254, v254, v240
	v_mul_f32_e32 v255, v255, v241
	v_mul_f32_e32 v254, v254, v78
	v_mul_f32_e32 v255, v255, v79
	v_cvt_pk_bf16_f32 v244, v254, v255
	v_lshlrev_b32_e32 v240, 16, v185
	v_and_b32_e32 v241, 0xffff0000, v185
	v_lshlrev_b32_e32 v242, 16, v189
	v_and_b32_e32 v243, 0xffff0000, v189
	v_lshlrev_b32_e32 v252, 16, v193
	v_and_b32_e32 v253, 0xffff0000, v193
	v_fma_f32 v254, v132, v240, v156
	v_fma_f32 v255, v133, v241, v157
	v_fma_f32 v254, v140, v242, v254
	v_fma_f32 v255, v141, v243, v255
	v_fma_f32 v254, v148, v252, v254
	v_fma_f32 v255, v149, v253, v255
	v_mul_f32_e32 v240, 0xbfb8aa3b, v254
	v_mul_f32_e32 v241, 0xbfb8aa3b, v255
	v_exp_f32_e32 v240, v240
	v_exp_f32_e32 v241, v241
	v_add_f32_e32 v240, 1.0, v240
	v_add_f32_e32 v241, 1.0, v241
	v_rcp_f32_e32 v240, v240
	v_rcp_f32_e32 v241, v241
	v_mul_f32_e32 v254, v254, v240
	v_mul_f32_e32 v255, v255, v241
	v_mul_f32_e32 v254, v254, v80
	v_mul_f32_e32 v255, v255, v81
	v_cvt_pk_bf16_f32 v245, v254, v255
	v_lshlrev_b32_e32 v240, 16, v186
	v_and_b32_e32 v241, 0xffff0000, v186
	v_lshlrev_b32_e32 v242, 16, v190
	v_and_b32_e32 v243, 0xffff0000, v190
	v_lshlrev_b32_e32 v252, 16, v194
	v_and_b32_e32 v253, 0xffff0000, v194
	v_fma_f32 v254, v134, v240, v158
	v_fma_f32 v255, v135, v241, v159
	v_fma_f32 v254, v142, v242, v254
	v_fma_f32 v255, v143, v243, v255
	v_fma_f32 v254, v150, v252, v254
	v_fma_f32 v255, v151, v253, v255
	v_mul_f32_e32 v240, 0xbfb8aa3b, v254
	v_mul_f32_e32 v241, 0xbfb8aa3b, v255
	v_exp_f32_e32 v240, v240
	v_exp_f32_e32 v241, v241
	v_add_f32_e32 v240, 1.0, v240
	v_add_f32_e32 v241, 1.0, v241
	v_rcp_f32_e32 v240, v240
	v_rcp_f32_e32 v241, v241
	v_mul_f32_e32 v254, v254, v240
	v_mul_f32_e32 v255, v255, v241
	v_mul_f32_e32 v254, v254, v74
	v_mul_f32_e32 v255, v255, v75
	v_cvt_pk_bf16_f32 v246, v254, v255
	v_lshlrev_b32_e32 v240, 16, v187
	v_and_b32_e32 v241, 0xffff0000, v187
	v_lshlrev_b32_e32 v242, 16, v191
	v_and_b32_e32 v243, 0xffff0000, v191
	v_lshlrev_b32_e32 v252, 16, v195
	v_and_b32_e32 v253, 0xffff0000, v195
	v_fma_f32 v254, v136, v240, v160
	v_fma_f32 v255, v137, v241, v161
	v_fma_f32 v254, v144, v242, v254
	v_fma_f32 v255, v145, v243, v255
	v_fma_f32 v254, v152, v252, v254
	v_fma_f32 v255, v153, v253, v255
	v_mul_f32_e32 v240, 0xbfb8aa3b, v254
	v_mul_f32_e32 v241, 0xbfb8aa3b, v255
	v_exp_f32_e32 v240, v240
	v_exp_f32_e32 v241, v241
	v_add_f32_e32 v240, 1.0, v240
	v_add_f32_e32 v241, 1.0, v241
	v_rcp_f32_e32 v240, v240
	v_rcp_f32_e32 v241, v241
	v_mul_f32_e32 v254, v254, v240
	v_mul_f32_e32 v255, v255, v241
	v_mul_f32_e32 v254, v254, v76
	v_mul_f32_e32 v255, v255, v77
	v_cvt_pk_bf16_f32 v247, v254, v255
	global_store_dwordx4 v[196:197], v[244:247], off offset:256
	v_add_u32_e32 v183, 0x7f, v176
	v_mad_i64_i32 v[222:223], s[0:1], v183, s14, v[180:181]
	v_lshl_add_u64 v[224:225], v[222:223], 0, s[98:99]
	v_lshl_add_u64 v[226:227], v[224:225], 0, s[98:99]
	v_lshl_add_u64 v[196:197], v[224:225], 0, s[100:101]
	global_load_dwordx4 v[184:187], v[222:223], off offset:256
	global_load_dwordx4 v[188:191], v[224:225], off offset:256
	global_load_dwordx4 v[192:195], v[226:227], off offset:256
	s_waitcnt vmcnt(4)
; DI unsigned pack2(float a, float b) { f32x2_t v = {a, b}; bf16x2_t r = __builtin_convertvector(v, bf16x2_t); return __builtin_bit_cast(unsigned, r); }
; DI float lo2f(unsigned u) { return __uint_as_float(u << 16); }
; DI float hi2f(unsigned u) { return __uint_as_float(u & 0xffff0000u); }
; DI float sigmoidf_(float x) { return __builtin_amdgcn_rcpf(1.f + __builtin_amdgcn_exp2f(-1.4426950408889634f * x)); }
;   DI void operator()(const f32x4 (&acc)[2][2][4][2], const pg8::Unit& u, int wr, int wc, int fr, int fq) const {
;     ...
;           for (int bj = 0; bj < 2; ++bj) {
;             const f32x4 v0 = acc[ai][bj][m][0], v1 = acc[ai][bj][m][1];
;             const uint4 g = gs[m][bj];
;             f32x4 q0 = {lo2f(g.x) * v0[0], hi2f(g.x) * v0[1], lo2f(g.y) * v0[2], hi2f(g.y) * v0[3]};
;             f32x4 q1 = {lo2f(g.z) * v1[0], hi2f(g.z) * v1[1], lo2f(g.w) * v1[2], hi2f(g.w) * v1[3]};
;             st8(o0 + (size_t)(row0 + ai * 128 + m * 16) * DFF + col0 + bj * 128, q0, q1);
; DI void conv_phase(const Params& p, int l) {
;     ...
;     for (int i = 0; i < RUN; ++i) {
;       unpack8(rows[i + 2], nxt);
;       float o[8];
; #pragma unroll
;       for (int j = 0; j < 8; ++j) { const float g = w0[j] * prev[j] + w1[j] * cur[j] + w2[j] * nxt[j] + bb[j]; o[j] = g * sigmoidf_(g); }
;       uint4 oo; oo.x = pack2(o[0], o[1]); oo.y = pack2(o[2], o[3]); oo.z = pack2(o[4], o[5]); oo.w = pack2(o[6], o[7]);
;       *(uint4*)(GS + (size_t)(t0 + i) * DFF + c0) = oo;
	v_lshlrev_b32_e32 v240, 16, v198
	v_and_b32_e32 v241, 0xffff0000, v198
	v_lshlrev_b32_e32 v242, 16, v202
	v_and_b32_e32 v243, 0xffff0000, v202
	v_lshlrev_b32_e32 v252, 16, v206
	v_and_b32_e32 v253, 0xffff0000, v206
	v_fma_f32 v254, v130, v240, v154
	v_fma_f32 v255, v131, v241, v155
	v_fma_f32 v254, v138, v242, v254
	v_fma_f32 v255, v139, v243, v255
	v_fma_f32 v254, v146, v252, v254
	v_fma_f32 v255, v147, v253, v255
	v_mul_f32_e32 v240, 0xbfb8aa3b, v254
	v_mul_f32_e32 v241, 0xbfb8aa3b, v255
	v_exp_f32_e32 v240, v240
	v_exp_f32_e32 v241, v241
	v_add_f32_e32 v240, 1.0, v240
	v_add_f32_e32 v241, 1.0, v241
	v_rcp_f32_e32 v240, v240
	v_rcp_f32_e32 v241, v241
	v_mul_f32_e32 v254, v254, v240
	v_mul_f32_e32 v255, v255, v241
	v_mul_f32_e32 v254, v254, v70
	v_mul_f32_e32 v255, v255, v71
	v_cvt_pk_bf16_f32 v248, v254, v255
	v_lshlrev_b32_e32 v240, 16, v199
	v_and_b32_e32 v241, 0xffff0000, v199
	v_lshlrev_b32_e32 v242, 16, v203
	v_and_b32_e32 v243, 0xffff0000, v203
	v_lshlrev_b32_e32 v252, 16, v207
	v_and_b32_e32 v253, 0xffff0000, v207
	v_fma_f32 v254, v132, v240, v156
	v_fma_f32 v255, v133, v241, v157
	v_fma_f32 v254, v140, v242, v254
	v_fma_f32 v255, v141, v243, v255
	v_fma_f32 v254, v148, v252, v254
	v_fma_f32 v255, v149, v253, v255
	v_mul_f32_e32 v240, 0xbfb8aa3b, v254
	v_mul_f32_e32 v241, 0xbfb8aa3b, v255
	v_exp_f32_e32 v240, v240
	v_exp_f32_e32 v241, v241
	v_add_f32_e32 v240, 1.0, v240
	v_add_f32_e32 v241, 1.0, v241
	v_rcp_f32_e32 v240, v240
	v_rcp_f32_e32 v241, v241
	v_mul_f32_e32 v254, v254, v240
	v_mul_f32_e32 v255, v255, v241
	v_mul_f32_e32 v254, v254, v72
	v_mul_f32_e32 v255, v255, v73
	v_cvt_pk_bf16_f32 v249, v254, v255
	v_lshlrev_b32_e32 v240, 16, v200
	v_and_b32_e32 v241, 0xffff0000, v200
	v_lshlrev_b32_e32 v242, 16, v204
	v_and_b32_e32 v243, 0xffff0000, v204
	v_lshlrev_b32_e32 v252, 16, v208
	v_and_b32_e32 v253, 0xffff0000, v208
	v_fma_f32 v254, v134, v240, v158
	v_fma_f32 v255, v135, v241, v159
	v_fma_f32 v254, v142, v242, v254
	v_fma_f32 v255, v143, v243, v255
	v_fma_f32 v254, v150, v252, v254
	v_fma_f32 v255, v151, v253, v255
	v_mul_f32_e32 v240, 0xbfb8aa3b, v254
	v_mul_f32_e32 v241, 0xbfb8aa3b, v255
	v_exp_f32_e32 v240, v240
	v_exp_f32_e32 v241, v241
	v_add_f32_e32 v240, 1.0, v240
	v_add_f32_e32 v241, 1.0, v241
	v_rcp_f32_e32 v240, v240
	v_rcp_f32_e32 v241, v241
	v_mul_f32_e32 v254, v254, v240
	v_mul_f32_e32 v255, v255, v241
	v_mul_f32_e32 v254, v254, v66
	v_mul_f32_e32 v255, v255, v67
	v_cvt_pk_bf16_f32 v250, v254, v255
	v_lshlrev_b32_e32 v240, 16, v201
	v_and_b32_e32 v241, 0xffff0000, v201
	v_lshlrev_b32_e32 v242, 16, v205
	v_and_b32_e32 v243, 0xffff0000, v205
	v_lshlrev_b32_e32 v252, 16, v209
	v_and_b32_e32 v253, 0xffff0000, v209
	v_fma_f32 v254, v136, v240, v160
	v_fma_f32 v255, v137, v241, v161
	v_fma_f32 v254, v144, v242, v254
	v_fma_f32 v255, v145, v243, v255
	v_fma_f32 v254, v152, v252, v254
	v_fma_f32 v255, v153, v253, v255
	v_mul_f32_e32 v240, 0xbfb8aa3b, v254
	v_mul_f32_e32 v241, 0xbfb8aa3b, v255
	v_exp_f32_e32 v240, v240
	v_exp_f32_e32 v241, v241
	v_add_f32_e32 v240, 1.0, v240
	v_add_f32_e32 v241, 1.0, v241
	v_rcp_f32_e32 v240, v240
	v_rcp_f32_e32 v241, v241
	v_mul_f32_e32 v254, v254, v240
	v_mul_f32_e32 v255, v255, v241
	v_mul_f32_e32 v254, v254, v68
	v_mul_f32_e32 v255, v255, v69
	v_cvt_pk_bf16_f32 v251, v254, v255
	global_store_dwordx4 v[220:221], v[248:251], off offset:256
	v_add_u32_e32 v183, 0x8f, v176
	v_mad_i64_i32 v[222:223], s[0:1], v183, s14, v[180:181]
	v_lshl_add_u64 v[224:225], v[222:223], 0, s[98:99]
	v_lshl_add_u64 v[226:227], v[224:225], 0, s[98:99]
	v_lshl_add_u64 v[220:221], v[224:225], 0, s[100:101]
	global_load_dwordx4 v[198:201], v[222:223], off offset:256
	global_load_dwordx4 v[202:205], v[224:225], off offset:256
	global_load_dwordx4 v[206:209], v[226:227], off offset:256
	s_waitcnt vmcnt(4)
	v_lshlrev_b32_e32 v240, 16, v184
	v_and_b32_e32 v241, 0xffff0000, v184
	v_lshlrev_b32_e32 v242, 16, v188
	v_and_b32_e32 v243, 0xffff0000, v188
	v_lshlrev_b32_e32 v252, 16, v192
	v_and_b32_e32 v253, 0xffff0000, v192
	v_fma_f32 v254, v130, v240, v154
	v_fma_f32 v255, v131, v241, v155
	v_fma_f32 v254, v138, v242, v254
	v_fma_f32 v255, v139, v243, v255
	v_fma_f32 v254, v146, v252, v254
	v_fma_f32 v255, v147, v253, v255
	v_mul_f32_e32 v240, 0xbfb8aa3b, v254
	v_mul_f32_e32 v241, 0xbfb8aa3b, v255
	v_exp_f32_e32 v240, v240
	v_exp_f32_e32 v241, v241
	v_add_f32_e32 v240, 1.0, v240
	v_add_f32_e32 v241, 1.0, v241
	v_rcp_f32_e32 v240, v240
	v_rcp_f32_e32 v241, v241
	v_mul_f32_e32 v254, v254, v240
	v_mul_f32_e32 v255, v255, v241
	v_mul_f32_e32 v254, v254, v46
	v_mul_f32_e32 v255, v255, v47
	v_cvt_pk_bf16_f32 v244, v254, v255
	v_lshlrev_b32_e32 v240, 16, v185
	v_and_b32_e32 v241, 0xffff0000, v185
	v_lshlrev_b32_e32 v242, 16, v189
	v_and_b32_e32 v243, 0xffff0000, v189
	v_lshlrev_b32_e32 v252, 16, v193
	v_and_b32_e32 v253, 0xffff0000, v193
	v_fma_f32 v254, v132, v240, v156
	v_fma_f32 v255, v133, v241, v157
	v_fma_f32 v254, v140, v242, v254
	v_fma_f32 v255, v141, v243, v255
	v_fma_f32 v254, v148, v252, v254
	v_fma_f32 v255, v149, v253, v255
	v_mul_f32_e32 v240, 0xbfb8aa3b, v254
	v_mul_f32_e32 v241, 0xbfb8aa3b, v255
	v_exp_f32_e32 v240, v240
	v_exp_f32_e32 v241, v241
	v_add_f32_e32 v240, 1.0, v240
	v_add_f32_e32 v241, 1.0, v241
	v_rcp_f32_e32 v240, v240
	v_rcp_f32_e32 v241, v241
	v_mul_f32_e32 v254, v254, v240
	v_mul_f32_e32 v255, v255, v241
	v_mul_f32_e32 v254, v254, v48
	v_mul_f32_e32 v255, v255, v49
	v_cvt_pk_bf16_f32 v245, v254, v255
	v_lshlrev_b32_e32 v240, 16, v186
	v_and_b32_e32 v241, 0xffff0000, v186
	v_lshlrev_b32_e32 v242, 16, v190
	v_and_b32_e32 v243, 0xffff0000, v190
	v_lshlrev_b32_e32 v252, 16, v194
; DI unsigned pack2(float a, float b) { f32x2_t v = {a, b}; bf16x2_t r = __builtin_convertvector(v, bf16x2_t); return __builtin_bit_cast(unsigned, r); }
; DI float lo2f(unsigned u) { return __uint_as_float(u << 16); }
; DI float hi2f(unsigned u) { return __uint_as_float(u & 0xffff0000u); }
; DI float sigmoidf_(float x) { return __builtin_amdgcn_rcpf(1.f + __builtin_amdgcn_exp2f(-1.4426950408889634f * x)); }
;   DI void operator()(const f32x4 (&acc)[2][2][4][2], const pg8::Unit& u, int wr, int wc, int fr, int fq) const {
;     ...
;           for (int bj = 0; bj < 2; ++bj) {
;             const f32x4 v0 = acc[ai][bj][m][0], v1 = acc[ai][bj][m][1];
;             const uint4 g = gs[m][bj];
;             f32x4 q0 = {lo2f(g.x) * v0[0], hi2f(g.x) * v0[1], lo2f(g.y) * v0[2], hi2f(g.y) * v0[3]};
;             f32x4 q1 = {lo2f(g.z) * v1[0], hi2f(g.z) * v1[1], lo2f(g.w) * v1[2], hi2f(g.w) * v1[3]};
;             st8(o0 + (size_t)(row0 + ai * 128 + m * 16) * DFF + col0 + bj * 128, q0, q1);
; DI void conv_phase(const Params& p, int l) {
;     ...
;     for (int i = 0; i < RUN; ++i) {
;       unpack8(rows[i + 2], nxt);
;       float o[8];
; #pragma unroll
;       for (int j = 0; j < 8; ++j) { const float g = w0[j] * prev[j] + w1[j] * cur[j] + w2[j] * nxt[j] + bb[j]; o[j] = g * sigmoidf_(g); }
;       uint4 oo; oo.x = pack2(o[0], o[1]); oo.y = pack2(o[2], o[3]); oo.z = pack2(o[4], o[5]); oo.w = pack2(o[6], o[7]);
;       *(uint4*)(GS + (size_t)(t0 + i) * DFF + c0) = oo;
	v_and_b32_e32 v253, 0xffff0000, v194
	v_fma_f32 v254, v134, v240, v158
	v_fma_f32 v255, v135, v241, v159
	v_fma_f32 v254, v142, v242, v254
	v_fma_f32 v255, v143, v243, v255
	v_fma_f32 v254, v150, v252, v254
	v_fma_f32 v255, v151, v253, v255
	v_mul_f32_e32 v240, 0xbfb8aa3b, v254
	v_mul_f32_e32 v241, 0xbfb8aa3b, v255
	v_exp_f32_e32 v240, v240
	v_exp_f32_e32 v241, v241
	v_add_f32_e32 v240, 1.0, v240
	v_add_f32_e32 v241, 1.0, v241
	v_rcp_f32_e32 v240, v240
	v_rcp_f32_e32 v241, v241
	v_mul_f32_e32 v254, v254, v240
	v_mul_f32_e32 v255, v255, v241
	v_mul_f32_e32 v254, v254, v42
	v_mul_f32_e32 v255, v255, v43
	v_cvt_pk_bf16_f32 v246, v254, v255
	v_lshlrev_b32_e32 v240, 16, v187
	v_and_b32_e32 v241, 0xffff0000, v187
	v_lshlrev_b32_e32 v242, 16, v191
	v_and_b32_e32 v243, 0xffff0000, v191
	v_lshlrev_b32_e32 v252, 16, v195
	v_and_b32_e32 v253, 0xffff0000, v195
	v_fma_f32 v254, v136, v240, v160
	v_fma_f32 v255, v137, v241, v161
	v_fma_f32 v254, v144, v242, v254
	v_fma_f32 v255, v145, v243, v255
	v_fma_f32 v254, v152, v252, v254
	v_fma_f32 v255, v153, v253, v255
	v_mul_f32_e32 v240, 0xbfb8aa3b, v254
	v_mul_f32_e32 v241, 0xbfb8aa3b, v255
	v_exp_f32_e32 v240, v240
	v_exp_f32_e32 v241, v241
	v_add_f32_e32 v240, 1.0, v240
	v_add_f32_e32 v241, 1.0, v241
	v_rcp_f32_e32 v240, v240
	v_rcp_f32_e32 v241, v241
	v_mul_f32_e32 v254, v254, v240
	v_mul_f32_e32 v255, v255, v241
	v_mul_f32_e32 v254, v254, v44
	v_mul_f32_e32 v255, v255, v45
	v_cvt_pk_bf16_f32 v247, v254, v255
	global_store_dwordx4 v[196:197], v[244:247], off offset:256
	v_add_u32_e32 v183, 0x9f, v176
	v_mad_i64_i32 v[222:223], s[0:1], v183, s14, v[180:181]
	v_lshl_add_u64 v[224:225], v[222:223], 0, s[98:99]
	v_lshl_add_u64 v[226:227], v[224:225], 0, s[98:99]
	v_lshl_add_u64 v[196:197], v[224:225], 0, s[100:101]
	global_load_dwordx4 v[184:187], v[222:223], off offset:256
	global_load_dwordx4 v[188:191], v[224:225], off offset:256
	global_load_dwordx4 v[192:195], v[226:227], off offset:256
	s_waitcnt vmcnt(4)
	v_lshlrev_b32_e32 v240, 16, v198
	v_and_b32_e32 v241, 0xffff0000, v198
	v_lshlrev_b32_e32 v242, 16, v202
	v_and_b32_e32 v243, 0xffff0000, v202
	v_lshlrev_b32_e32 v252, 16, v206
	v_and_b32_e32 v253, 0xffff0000, v206
	v_fma_f32 v254, v130, v240, v154
	v_fma_f32 v255, v131, v241, v155
	v_fma_f32 v254, v138, v242, v254
	v_fma_f32 v255, v139, v243, v255
	v_fma_f32 v254, v146, v252, v254
	v_fma_f32 v255, v147, v253, v255
	v_mul_f32_e32 v240, 0xbfb8aa3b, v254
	v_mul_f32_e32 v241, 0xbfb8aa3b, v255
	v_exp_f32_e32 v240, v240
	v_exp_f32_e32 v241, v241
	v_add_f32_e32 v240, 1.0, v240
	v_add_f32_e32 v241, 1.0, v241
	v_rcp_f32_e32 v240, v240
	v_rcp_f32_e32 v241, v241
	v_mul_f32_e32 v254, v254, v240
	v_mul_f32_e32 v255, v255, v241
	v_mul_f32_e32 v254, v254, v30
	v_mul_f32_e32 v255, v255, v31
	v_cvt_pk_bf16_f32 v248, v254, v255
	v_lshlrev_b32_e32 v240, 16, v199
	v_and_b32_e32 v241, 0xffff0000, v199
	v_lshlrev_b32_e32 v242, 16, v203
	v_and_b32_e32 v243, 0xffff0000, v203
	v_lshlrev_b32_e32 v252, 16, v207
	v_and_b32_e32 v253, 0xffff0000, v207
	v_fma_f32 v254, v132, v240, v156
	v_fma_f32 v255, v133, v241, v157
	v_fma_f32 v254, v140, v242, v254
	v_fma_f32 v255, v141, v243, v255
	v_fma_f32 v254, v148, v252, v254
	v_fma_f32 v255, v149, v253, v255
	v_mul_f32_e32 v240, 0xbfb8aa3b, v254
	v_mul_f32_e32 v241, 0xbfb8aa3b, v255
	v_exp_f32_e32 v240, v240
	v_exp_f32_e32 v241, v241
	v_add_f32_e32 v240, 1.0, v240
	v_add_f32_e32 v241, 1.0, v241
	v_rcp_f32_e32 v240, v240
	v_rcp_f32_e32 v241, v241
	v_mul_f32_e32 v254, v254, v240
	v_mul_f32_e32 v255, v255, v241
	v_mul_f32_e32 v254, v254, v32
	v_mul_f32_e32 v255, v255, v33
	v_cvt_pk_bf16_f32 v249, v254, v255
	v_lshlrev_b32_e32 v240, 16, v200
	v_and_b32_e32 v241, 0xffff0000, v200
	v_lshlrev_b32_e32 v242, 16, v204
	v_and_b32_e32 v243, 0xffff0000, v204
	v_lshlrev_b32_e32 v252, 16, v208
	v_and_b32_e32 v253, 0xffff0000, v208
	v_fma_f32 v254, v134, v240, v158
	v_fma_f32 v255, v135, v241, v159
	v_fma_f32 v254, v142, v242, v254
	v_fma_f32 v255, v143, v243, v255
	v_fma_f32 v254, v150, v252, v254
	v_fma_f32 v255, v151, v253, v255
	v_mul_f32_e32 v240, 0xbfb8aa3b, v254
	v_mul_f32_e32 v241, 0xbfb8aa3b, v255
	v_exp_f32_e32 v240, v240
	v_exp_f32_e32 v241, v241
	v_add_f32_e32 v240, 1.0, v240
	v_add_f32_e32 v241, 1.0, v241
	v_rcp_f32_e32 v240, v240
	v_rcp_f32_e32 v241, v241
	v_mul_f32_e32 v254, v254, v240
	v_mul_f32_e32 v255, v255, v241
	v_mul_f32_e32 v254, v254, v26
	v_mul_f32_e32 v255, v255, v27
	v_cvt_pk_bf16_f32 v250, v254, v255
	v_lshlrev_b32_e32 v240, 16, v201
	v_and_b32_e32 v241, 0xffff0000, v201
	v_lshlrev_b32_e32 v242, 16, v205
	v_and_b32_e32 v243, 0xffff0000, v205
	v_lshlrev_b32_e32 v252, 16, v209
	v_and_b32_e32 v253, 0xffff0000, v209
	v_fma_f32 v254, v136, v240, v160
	v_fma_f32 v255, v137, v241, v161
	v_fma_f32 v254, v144, v242, v254
	v_fma_f32 v255, v145, v243, v255
	v_fma_f32 v254, v152, v252, v254
	v_fma_f32 v255, v153, v253, v255
	v_mul_f32_e32 v240, 0xbfb8aa3b, v254
	v_mul_f32_e32 v241, 0xbfb8aa3b, v255
	v_exp_f32_e32 v240, v240
	v_exp_f32_e32 v241, v241
	v_add_f32_e32 v240, 1.0, v240
	v_add_f32_e32 v241, 1.0, v241
	v_rcp_f32_e32 v240, v240
	v_rcp_f32_e32 v241, v241
	v_mul_f32_e32 v254, v254, v240
	v_mul_f32_e32 v255, v255, v241
	v_mul_f32_e32 v254, v254, v28
	v_mul_f32_e32 v255, v255, v29
	v_cvt_pk_bf16_f32 v251, v254, v255
	global_store_dwordx4 v[220:221], v[248:251], off offset:256
	v_add_u32_e32 v183, 0xaf, v176
	v_mad_i64_i32 v[222:223], s[0:1], v183, s14, v[180:181]
	v_lshl_add_u64 v[224:225], v[222:223], 0, s[98:99]
	v_lshl_add_u64 v[226:227], v[224:225], 0, s[98:99]
	v_lshl_add_u64 v[220:221], v[224:225], 0, s[100:101]
	global_load_dwordx4 v[198:201], v[222:223], off offset:256
	global_load_dwordx4 v[202:205], v[224:225], off offset:256
	global_load_dwordx4 v[206:209], v[226:227], off offset:256
	s_waitcnt vmcnt(4)
; DI unsigned pack2(float a, float b) { f32x2_t v = {a, b}; bf16x2_t r = __builtin_convertvector(v, bf16x2_t); return __builtin_bit_cast(unsigned, r); }
; DI float lo2f(unsigned u) { return __uint_as_float(u << 16); }
; DI float hi2f(unsigned u) { return __uint_as_float(u & 0xffff0000u); }
; DI float sigmoidf_(float x) { return __builtin_amdgcn_rcpf(1.f + __builtin_amdgcn_exp2f(-1.4426950408889634f * x)); }
;   DI void operator()(const f32x4 (&acc)[2][2][4][2], const pg8::Unit& u, int wr, int wc, int fr, int fq) const {
;     ...
;           for (int bj = 0; bj < 2; ++bj) {
;             const f32x4 v0 = acc[ai][bj][m][0], v1 = acc[ai][bj][m][1];
;             const uint4 g = gs[m][bj];
;             f32x4 q0 = {lo2f(g.x) * v0[0], hi2f(g.x) * v0[1], lo2f(g.y) * v0[2], hi2f(g.y) * v0[3]};
;             f32x4 q1 = {lo2f(g.z) * v1[0], hi2f(g.z) * v1[1], lo2f(g.w) * v1[2], hi2f(g.w) * v1[3]};
;             st8(o0 + (size_t)(row0 + ai * 128 + m * 16) * DFF + col0 + bj * 128, q0, q1);
; DI void conv_phase(const Params& p, int l) {
;     ...
;     rows[RUN + 1] = (s0 + RUN - 1 < S - 1) ? *(const uint4*)(gp + (size_t)RUN * DFF) : z;
;     float w0[8], w1[8], w2[8], bb[8];
;     load8f(cw + c0, w0); load8f(cw + DFF + c0, w1); load8f(cw + 2 * DFF + c0, w2); load8f(cb + c0, bb);
;     float prev[8], cur[8], nxt[8];
;     unpack8(rows[0], prev); unpack8(rows[1], cur);
; #pragma unroll
;     for (int i = 0; i < RUN; ++i) {
;       unpack8(rows[i + 2], nxt);
;       float o[8];
; #pragma unroll
;       for (int j = 0; j < 8; ++j) { const float g = w0[j] * prev[j] + w1[j] * cur[j] + w2[j] * nxt[j] + bb[j]; o[j] = g * sigmoidf_(g); }
;       uint4 oo; oo.x = pack2(o[0], o[1]); oo.y = pack2(o[2], o[3]); oo.z = pack2(o[4], o[5]); oo.w = pack2(o[6], o[7]);
;       *(uint4*)(GS + (size_t)(t0 + i) * DFF + c0) = oo;
	v_lshlrev_b32_e32 v240, 16, v184
	v_and_b32_e32 v241, 0xffff0000, v184
	v_lshlrev_b32_e32 v242, 16, v188
	v_and_b32_e32 v243, 0xffff0000, v188
	v_lshlrev_b32_e32 v252, 16, v192
	v_and_b32_e32 v253, 0xffff0000, v192
	v_fma_f32 v254, v130, v240, v154
	v_fma_f32 v255, v131, v241, v155
	v_fma_f32 v254, v138, v242, v254
	v_fma_f32 v255, v139, v243, v255
	v_fma_f32 v254, v146, v252, v254
	v_fma_f32 v255, v147, v253, v255
	v_mul_f32_e32 v240, 0xbfb8aa3b, v254
	v_mul_f32_e32 v241, 0xbfb8aa3b, v255
	v_exp_f32_e32 v240, v240
	v_exp_f32_e32 v241, v241
	v_add_f32_e32 v240, 1.0, v240
	v_add_f32_e32 v241, 1.0, v241
	v_rcp_f32_e32 v240, v240
	v_rcp_f32_e32 v241, v241
	v_mul_f32_e32 v254, v254, v240
	v_mul_f32_e32 v255, v255, v241
	v_mul_f32_e32 v254, v254, v14
	v_mul_f32_e32 v255, v255, v15
	v_cvt_pk_bf16_f32 v244, v254, v255
	v_lshlrev_b32_e32 v240, 16, v185
	v_and_b32_e32 v241, 0xffff0000, v185
	v_lshlrev_b32_e32 v242, 16, v189
	v_and_b32_e32 v243, 0xffff0000, v189
	v_lshlrev_b32_e32 v252, 16, v193
	v_and_b32_e32 v253, 0xffff0000, v193
	v_fma_f32 v254, v132, v240, v156
	v_fma_f32 v255, v133, v241, v157
	v_fma_f32 v254, v140, v242, v254
	v_fma_f32 v255, v141, v243, v255
	v_fma_f32 v254, v148, v252, v254
	v_fma_f32 v255, v149, v253, v255
	v_mul_f32_e32 v240, 0xbfb8aa3b, v254
	v_mul_f32_e32 v241, 0xbfb8aa3b, v255
	v_exp_f32_e32 v240, v240
	v_exp_f32_e32 v241, v241
	v_add_f32_e32 v240, 1.0, v240
	v_add_f32_e32 v241, 1.0, v241
	v_rcp_f32_e32 v240, v240
	v_rcp_f32_e32 v241, v241
	v_mul_f32_e32 v254, v254, v240
	v_mul_f32_e32 v255, v255, v241
	v_mul_f32_e32 v254, v254, v16
	v_mul_f32_e32 v255, v255, v17
	v_cvt_pk_bf16_f32 v245, v254, v255
	v_lshlrev_b32_e32 v240, 16, v186
	v_and_b32_e32 v241, 0xffff0000, v186
	v_lshlrev_b32_e32 v242, 16, v190
	v_and_b32_e32 v243, 0xffff0000, v190
	v_lshlrev_b32_e32 v252, 16, v194
	v_and_b32_e32 v253, 0xffff0000, v194
	v_fma_f32 v254, v134, v240, v158
	v_fma_f32 v255, v135, v241, v159
	v_fma_f32 v254, v142, v242, v254
	v_fma_f32 v255, v143, v243, v255
	v_fma_f32 v254, v150, v252, v254
	v_fma_f32 v255, v151, v253, v255
	v_mul_f32_e32 v240, 0xbfb8aa3b, v254
	v_mul_f32_e32 v241, 0xbfb8aa3b, v255
	v_exp_f32_e32 v240, v240
	v_exp_f32_e32 v241, v241
	v_add_f32_e32 v240, 1.0, v240
	v_add_f32_e32 v241, 1.0, v241
	v_rcp_f32_e32 v240, v240
	v_rcp_f32_e32 v241, v241
	v_mul_f32_e32 v254, v254, v240
	v_mul_f32_e32 v255, v255, v241
	v_mul_f32_e32 v254, v254, v10
	v_mul_f32_e32 v255, v255, v11
	v_cvt_pk_bf16_f32 v246, v254, v255
	v_lshlrev_b32_e32 v240, 16, v187
	v_and_b32_e32 v241, 0xffff0000, v187
	v_lshlrev_b32_e32 v242, 16, v191
	v_and_b32_e32 v243, 0xffff0000, v191
	v_lshlrev_b32_e32 v252, 16, v195
	v_and_b32_e32 v253, 0xffff0000, v195
	v_fma_f32 v254, v136, v240, v160
	v_fma_f32 v255, v137, v241, v161
	v_fma_f32 v254, v144, v242, v254
	v_fma_f32 v255, v145, v243, v255
	v_fma_f32 v254, v152, v252, v254
	v_fma_f32 v255, v153, v253, v255
	v_mul_f32_e32 v240, 0xbfb8aa3b, v254
	v_mul_f32_e32 v241, 0xbfb8aa3b, v255
	v_exp_f32_e32 v240, v240
	v_exp_f32_e32 v241, v241
	v_add_f32_e32 v240, 1.0, v240
	v_add_f32_e32 v241, 1.0, v241
	v_rcp_f32_e32 v240, v240
	v_rcp_f32_e32 v241, v241
	v_mul_f32_e32 v254, v254, v240
	v_mul_f32_e32 v255, v255, v241
	v_mul_f32_e32 v254, v254, v12
	v_mul_f32_e32 v255, v255, v13
	v_cvt_pk_bf16_f32 v247, v254, v255
	global_store_dwordx4 v[196:197], v[244:247], off offset:256
	s_waitcnt vmcnt(1)
	v_add_u32_e32 v183, 0xb0, v176
	v_and_b32_e32 v183, 0x1fff, v183
	v_cmp_eq_u32_e32 vcc, 0x1fff, v183
	v_cndmask_b32_e64 v206, v206, 0, vcc
	v_cndmask_b32_e64 v207, v207, 0, vcc
	v_cndmask_b32_e64 v208, v208, 0, vcc
	v_cndmask_b32_e64 v209, v209, 0, vcc
	v_lshlrev_b32_e32 v240, 16, v198
	v_and_b32_e32 v241, 0xffff0000, v198
	v_lshlrev_b32_e32 v242, 16, v202
	v_and_b32_e32 v243, 0xffff0000, v202
	v_lshlrev_b32_e32 v252, 16, v206
	v_and_b32_e32 v253, 0xffff0000, v206
	v_fma_f32 v254, v130, v240, v154
	v_fma_f32 v255, v131, v241, v155
	v_fma_f32 v254, v138, v242, v254
	v_fma_f32 v255, v139, v243, v255
	v_fma_f32 v254, v146, v252, v254
	v_fma_f32 v255, v147, v253, v255
	v_mul_f32_e32 v240, 0xbfb8aa3b, v254
	v_mul_f32_e32 v241, 0xbfb8aa3b, v255
	v_exp_f32_e32 v240, v240
	v_exp_f32_e32 v241, v241
	v_add_f32_e32 v240, 1.0, v240
	v_add_f32_e32 v241, 1.0, v241
	v_rcp_f32_e32 v240, v240
	v_rcp_f32_e32 v241, v241
	v_mul_f32_e32 v254, v254, v240
	v_mul_f32_e32 v255, v255, v241
	v_mul_f32_e32 v254, v254, v6
	v_mul_f32_e32 v255, v255, v7
	v_cvt_pk_bf16_f32 v248, v254, v255
	v_lshlrev_b32_e32 v240, 16, v199
	v_and_b32_e32 v241, 0xffff0000, v199
	v_lshlrev_b32_e32 v242, 16, v203
	v_and_b32_e32 v243, 0xffff0000, v203
	v_lshlrev_b32_e32 v252, 16, v207
	v_and_b32_e32 v253, 0xffff0000, v207
	v_fma_f32 v254, v132, v240, v156
	v_fma_f32 v255, v133, v241, v157
	v_fma_f32 v254, v140, v242, v254
	v_fma_f32 v255, v141, v243, v255
	v_fma_f32 v254, v148, v252, v254
	v_fma_f32 v255, v149, v253, v255
	v_mul_f32_e32 v240, 0xbfb8aa3b, v254
	v_mul_f32_e32 v241, 0xbfb8aa3b, v255
	v_exp_f32_e32 v240, v240
	v_exp_f32_e32 v241, v241
	v_add_f32_e32 v240, 1.0, v240
	v_add_f32_e32 v241, 1.0, v241
	v_rcp_f32_e32 v240, v240
	v_rcp_f32_e32 v241, v241
	v_mul_f32_e32 v254, v254, v240
	v_mul_f32_e32 v255, v255, v241
	v_mul_f32_e32 v254, v254, v8
	v_mul_f32_e32 v255, v255, v9
	v_cvt_pk_bf16_f32 v249, v254, v255
	v_lshlrev_b32_e32 v240, 16, v200
	v_and_b32_e32 v241, 0xffff0000, v200
	v_lshlrev_b32_e32 v242, 16, v204
	v_and_b32_e32 v243, 0xffff0000, v204
	v_lshlrev_b32_e32 v252, 16, v208
	v_and_b32_e32 v253, 0xffff0000, v208
	v_fma_f32 v254, v134, v240, v158
	v_fma_f32 v255, v135, v241, v159
	v_fma_f32 v254, v142, v242, v254
	v_fma_f32 v255, v143, v243, v255
	v_fma_f32 v254, v150, v252, v254
	v_fma_f32 v255, v151, v253, v255
	v_mul_f32_e32 v240, 0xbfb8aa3b, v254
	v_mul_f32_e32 v241, 0xbfb8aa3b, v255
	v_exp_f32_e32 v240, v240
	v_exp_f32_e32 v241, v241
	v_add_f32_e32 v240, 1.0, v240
	v_add_f32_e32 v241, 1.0, v241
	v_rcp_f32_e32 v240, v240
	v_rcp_f32_e32 v241, v241
	v_mul_f32_e32 v254, v254, v240
	v_mul_f32_e32 v255, v255, v241
	v_mul_f32_e32 v254, v254, v2
	v_mul_f32_e32 v255, v255, v3
	v_cvt_pk_bf16_f32 v250, v254, v255
	v_lshlrev_b32_e32 v240, 16, v201
	v_and_b32_e32 v241, 0xffff0000, v201
	v_lshlrev_b32_e32 v242, 16, v205
	v_and_b32_e32 v243, 0xffff0000, v205
	v_lshlrev_b32_e32 v252, 16, v209
	v_and_b32_e32 v253, 0xffff0000, v209
	v_fma_f32 v254, v136, v240, v160
	v_fma_f32 v255, v137, v241, v161
	v_fma_f32 v254, v144, v242, v254
	v_fma_f32 v255, v145, v243, v255
	v_fma_f32 v254, v152, v252, v254
	v_fma_f32 v255, v153, v253, v255
	v_mul_f32_e32 v240, 0xbfb8aa3b, v254
	v_mul_f32_e32 v241, 0xbfb8aa3b, v255
	v_exp_f32_e32 v240, v240
	v_exp_f32_e32 v241, v241
	v_add_f32_e32 v240, 1.0, v240
	v_add_f32_e32 v241, 1.0, v241
	v_rcp_f32_e32 v240, v240
	v_rcp_f32_e32 v241, v241
	v_mul_f32_e32 v254, v254, v240
	v_mul_f32_e32 v255, v255, v241
	v_mul_f32_e32 v254, v254, v4
	v_mul_f32_e32 v255, v255, v5
	v_cvt_pk_bf16_f32 v251, v254, v255
	global_store_dwordx4 v[220:221], v[248:251], off offset:256
	s_mov_b64 s[0:1], 0
